# P0 rows: dlr projection on f32 MFMA (16x16x4), 16-row batches, W slice in registers; plus seam edits
# speedup vs baseline: 1.0135x; 1.0064x over previous
; __device__ __forceinline__ float wave_sum(float v) { for (int o = 32; o >= 1; o >>= 1) v += __shfl_xor(v, o); return v; }
; __device__ __forceinline__ void p0_rows(const Args& a, LAS unsigned char* lds, int gw, int NGW, int wave, int lane, int tid) {
;     ...
;     for (int idx = tid; idx < 1024 * 16; idx += 512) { const int k = idx >> 4, j = idx & 15; WdL[(k >> 8) * 4112 + (k & 255) * 16 + j] = a.in[I_WIN][(size_t)k * DIN + 4608 + j]; }
;     __syncthreads();
;     bf16_t* H = (bf16_t*)((unsigned char*)a.out + Y_H); float* DLR = (float*)((unsigned char*)a.out + Y_DLR);
;     const f32x4* gp = (const f32x4*)a.in[I_NMPRE] + lane; f32x4 g[4];
; #pragma unroll
;     for (int j = 0; j < 4; ++j) g[j] = gp[64 * j];
;     for (int row = gw; row < MT; row += NGW) {
;         const f32x4* xr = (const f32x4*)xrow_ptr(a, row) + lane; f32x4 v[4]; float s = 0.f;
; #pragma unroll
;         for (int j = 0; j < 4; ++j) { v[j] = xr[64 * j]; s += (v[j][0] * v[j][0] + v[j][1] * v[j][1]) + (v[j][2] * v[j][2] + v[j][3] * v[j][3]); }
;         const float rstd = rsqrtf(wave_sum(s) * (1.f / DM) + EPS);
.LBB0_129:
	s_cmpk_lg_i32 s58, 0x100
	s_cbranch_scc1 .Lp0m_generic
	v_lshlrev_b32_e32 v28, 4, v176
	v_lshlrev_b32_e32 v29, 3, v176
	v_mov_b32_e32 v16, 0x358637bd
	v_mov_b32_e32 v17, v28
	v_and_b32_e32 v30, 15, v176
	v_lshrrev_b32_e32 v31, 4, v176
	v_readlane_b32 s36, v252, 1
	v_readlane_b32 s37, v252, 2
	v_readlane_b32 s38, v252, 3
	v_readlane_b32 s39, v252, 4
	v_readlane_b32 s46, v252, 11
	v_readlane_b32 s47, v252, 12
	s_mov_b32 s3, 0x800000
	s_mul_i32 s42, s93, 0x1010
	s_nop 4
	global_load_dwordx4 v[0:3], v28, s[46:47]
	global_load_dwordx4 v[4:7], v28, s[46:47] offset:1024
	global_load_dwordx4 v[8:11], v28, s[46:47] offset:2048
	global_load_dwordx4 v[12:15], v28, s[46:47] offset:3072
	s_lshl_b32 s10, s81, 12
	s_add_u32 s44, s36, s10
	s_addc_u32 s45, s37, 0
	global_load_dwordx4 v[32:35], v28, s[44:45]
	global_load_dwordx4 v[36:39], v28, s[44:45] offset:1024
	global_load_dwordx4 v[40:43], v28, s[44:45] offset:2048
	global_load_dwordx4 v[44:47], v28, s[44:45] offset:3072
	s_add_u32 s10, s44, 0x800000
	s_addc_u32 s11, s45, 0
	global_load_dwordx4 v[48:51], v28, s[10:11]
	global_load_dwordx4 v[52:55], v28, s[10:11] offset:1024
	global_load_dwordx4 v[56:59], v28, s[10:11] offset:2048
	global_load_dwordx4 v[60:63], v28, s[10:11] offset:3072
	s_lshl_b32 s10, s81, 11
	s_add_u32 s40, s52, s10
	s_addc_u32 s41, s53, 0
	v_lshlrev_b32_e32 v24, 8, v31
	s_lshl_b32 s10, s93, 5
	v_add_u32_e32 v24, s10, v24
	v_mul_u32_u24_e32 v24, 0x1a10, v24
	v_add_u32_e32 v24, v24, v30
	v_add_u32_e32 v24, 0x1200, v24
	v_lshlrev_b32_e32 v24, 2, v24
	s_mov_b64 s[0:1], s[14:15]
	global_load_dword v96, v24, s[0:1]
	s_add_u32 s0, s0, 0x6840
	s_addc_u32 s1, s1, 0
	global_load_dword v97, v24, s[0:1]
	s_add_u32 s0, s0, 0x6840
	s_addc_u32 s1, s1, 0
	global_load_dword v98, v24, s[0:1]
	s_add_u32 s0, s0, 0x6840
	s_addc_u32 s1, s1, 0
	global_load_dword v99, v24, s[0:1]
	s_add_u32 s0, s0, 0x6840
	s_addc_u32 s1, s1, 0
	global_load_dword v100, v24, s[0:1]
	s_add_u32 s0, s0, 0x6840
	s_addc_u32 s1, s1, 0
	global_load_dword v101, v24, s[0:1]
	s_add_u32 s0, s0, 0x6840
	s_addc_u32 s1, s1, 0
	global_load_dword v102, v24, s[0:1]
	s_add_u32 s0, s0, 0x6840
	s_addc_u32 s1, s1, 0
	global_load_dword v103, v24, s[0:1]
	s_add_u32 s0, s0, 0x6840
	s_addc_u32 s1, s1, 0
	global_load_dword v104, v24, s[0:1]
	s_add_u32 s0, s0, 0x6840
	s_addc_u32 s1, s1, 0
	global_load_dword v105, v24, s[0:1]
	s_add_u32 s0, s0, 0x6840
	s_addc_u32 s1, s1, 0
	global_load_dword v106, v24, s[0:1]
	s_add_u32 s0, s0, 0x6840
	s_addc_u32 s1, s1, 0
	global_load_dword v107, v24, s[0:1]
	s_add_u32 s0, s0, 0x6840
	s_addc_u32 s1, s1, 0
	global_load_dword v108, v24, s[0:1]
	s_add_u32 s0, s0, 0x6840
	s_addc_u32 s1, s1, 0
	global_load_dword v109, v24, s[0:1]
	s_add_u32 s0, s0, 0x6840
	s_addc_u32 s1, s1, 0
	global_load_dword v110, v24, s[0:1]
	s_add_u32 s0, s0, 0x6840
	s_addc_u32 s1, s1, 0
	global_load_dword v111, v24, s[0:1]
	s_add_u32 s0, s0, 0x6840
	s_addc_u32 s1, s1, 0
	global_load_dword v112, v24, s[0:1]
	s_add_u32 s0, s0, 0x6840
	s_addc_u32 s1, s1, 0
	global_load_dword v113, v24, s[0:1]
	s_add_u32 s0, s0, 0x6840
	s_addc_u32 s1, s1, 0
	global_load_dword v114, v24, s[0:1]
	s_add_u32 s0, s0, 0x6840
	s_addc_u32 s1, s1, 0
	global_load_dword v115, v24, s[0:1]
	s_add_u32 s0, s0, 0x6840
	s_addc_u32 s1, s1, 0
	global_load_dword v116, v24, s[0:1]
	s_add_u32 s0, s0, 0x6840
	s_addc_u32 s1, s1, 0
	global_load_dword v117, v24, s[0:1]
	s_add_u32 s0, s0, 0x6840
	s_addc_u32 s1, s1, 0
	global_load_dword v118, v24, s[0:1]
	s_add_u32 s0, s0, 0x6840
	s_addc_u32 s1, s1, 0
	global_load_dword v119, v24, s[0:1]
	s_add_u32 s0, s0, 0x6840
	s_addc_u32 s1, s1, 0
	global_load_dword v120, v24, s[0:1]
	s_add_u32 s0, s0, 0x6840
	s_addc_u32 s1, s1, 0
	global_load_dword v121, v24, s[0:1]
	s_add_u32 s0, s0, 0x6840
	s_addc_u32 s1, s1, 0
	global_load_dword v122, v24, s[0:1]
	s_add_u32 s0, s0, 0x6840
	s_addc_u32 s1, s1, 0
	global_load_dword v123, v24, s[0:1]
	s_add_u32 s0, s0, 0x6840
	s_addc_u32 s1, s1, 0
	global_load_dword v124, v24, s[0:1]
	s_add_u32 s0, s0, 0x6840
	s_addc_u32 s1, s1, 0
	global_load_dword v125, v24, s[0:1]
	s_add_u32 s0, s0, 0x6840
	s_addc_u32 s1, s1, 0
	global_load_dword v126, v24, s[0:1]
	s_add_u32 s0, s0, 0x6840
	s_addc_u32 s1, s1, 0
	global_load_dword v127, v24, s[0:1]
	v_mul_u32_u24_e32 v19, 0x1010, v30
	v_lshlrev_b32_e32 v25, 10, v31
	s_lshl_b32 s10, s93, 7
	v_add3_u32 v19, v19, v25, s10
	v_add_u32_e32 v20, 0x10100, v19
	s_lshl_b32 s10, s93, 10
	s_add_i32 s10, s10, 0x20200
	v_add_u32_e32 v21, s10, v28
	v_and_b32_e32 v25, 3, v31
	s_lshl_b32 s10, s93, 8
	s_add_i32 s10, s10, 0x20200
	v_lshlrev_b32_e32 v22, 4, v30
	v_lshl_add_u32 v22, v25, 2, v22
	v_add_u32_e32 v22, s10, v22
	s_lshl_b32 s10, s93, 2
	v_add_u32_e32 v26, s10, v25
	v_and_b32_e32 v27, 7, v26
	v_lshrrev_b32_e32 v26, 3, v26
	v_lshl_add_u32 v27, v26, 11, v27
	s_lshl_b32 s10, s2, 3
	v_add_u32_e32 v27, s10, v27
	v_lshlrev_b32_e32 v27, 6, v27
	v_lshl_add_u32 v23, v30, 2, v27
	v_add_u32_e32 v23, 0x4000000, v23
	s_waitcnt lgkmcnt(0)
	s_barrier
; #define LAS __attribute__((address_space(3)))
; __device__ __forceinline__ float wave_sum(float v) { for (int o = 32; o >= 1; o >>= 1) v += __shfl_xor(v, o); return v; }
; __device__ __forceinline__ void wave_lds_sync() { asm volatile("s_waitcnt lgkmcnt(0)" ::: "memory"); __builtin_amdgcn_wave_barrier(); }
; __device__ __forceinline__ u32x2 pk4(f32x4 v) { u32x2 w; w.x = cvt_pk_bf16(v[0], v[1]); w.y = cvt_pk_bf16(v[2], v[3]); return w; }
; __device__ __forceinline__ void p0_rows(const Args& a, LAS unsigned char* lds, int gw, int NGW, int wave, int lane, int tid) {
;     ...
;         const f32x4* xr = (const f32x4*)xrow_ptr(a, row) + lane; f32x4 v[4]; float s = 0.f;
; #pragma unroll
;         for (int j = 0; j < 4; ++j) { v[j] = xr[64 * j]; s += (v[j][0] * v[j][0] + v[j][1] * v[j][1]) + (v[j][2] * v[j][2] + v[j][3] * v[j][3]); }
;         const float rstd = rsqrtf(wave_sum(s) * (1.f / DM) + EPS);
;         u32x2* ho = (u32x2*)(H + (size_t)row * DM) + lane;
; #pragma unroll
;         for (int j = 0; j < 4; ++j) { v[j] = v[j] * rstd * g[j]; ho[64 * j] = pk4(v[j]); *(LAS f32x4*)(hrow + j * 264 + 4 * lane) = v[j]; }
;         wave_lds_sync();
	s_add_u32 s44, s44, 0x1000000
	s_addc_u32 s45, s45, 0
	global_load_dwordx4 v[192:195], v28, s[44:45]
	global_load_dwordx4 v[196:199], v28, s[44:45] offset:1024
	global_load_dwordx4 v[200:203], v28, s[44:45] offset:2048
	global_load_dwordx4 v[204:207], v28, s[44:45] offset:3072
	s_add_u32 s10, s44, 0x800000
	s_addc_u32 s11, s45, 0
	global_load_dwordx4 v[208:211], v28, s[10:11]
	global_load_dwordx4 v[212:215], v28, s[10:11] offset:1024
	global_load_dwordx4 v[216:219], v28, s[10:11] offset:2048
	global_load_dwordx4 v[220:223], v28, s[10:11] offset:3072
	s_waitcnt vmcnt(40)
	v_mul_f32_e32 v64, v32, v32
	v_fmac_f32_e32 v64, v33, v33
	v_mul_f32_e32 v65, v34, v34
	v_fmac_f32_e32 v65, v35, v35
	v_add_f32_e32 v64, v64, v65
	v_mul_f32_e32 v66, v36, v36
	v_fmac_f32_e32 v66, v37, v37
	v_mul_f32_e32 v67, v38, v38
	v_fmac_f32_e32 v67, v39, v39
	v_add_f32_e32 v66, v66, v67
	v_mul_f32_e32 v68, v40, v40
	v_fmac_f32_e32 v68, v41, v41
	v_mul_f32_e32 v69, v42, v42
	v_fmac_f32_e32 v69, v43, v43
	v_add_f32_e32 v68, v68, v69
	v_mul_f32_e32 v70, v44, v44
	v_fmac_f32_e32 v70, v45, v45
	v_mul_f32_e32 v71, v46, v46
	v_fmac_f32_e32 v71, v47, v47
	v_add_f32_e32 v70, v70, v71
	v_add_f32_e32 v64, v64, v66
	v_add_f32_e32 v64, v64, v68
	v_add_f32_e32 v64, v64, v70
	s_nop 1
	v_add_f32_dpp v88, v64, v64 quad_perm:[1,0,3,2] row_mask:0xf bank_mask:0xf
	s_nop 1
	v_add_f32_dpp v88, v88, v88 quad_perm:[2,3,0,1] row_mask:0xf bank_mask:0xf
	s_nop 1
	v_add_f32_dpp v88, v88, v88 row_half_mirror row_mask:0xf bank_mask:0xf
	s_nop 1
	v_add_f32_dpp v88, v88, v88 row_mirror row_mask:0xf bank_mask:0xf
	s_nop 1
	v_readlane_b32 s48, v88, 0
	v_readlane_b32 s49, v88, 16
	v_readlane_b32 s50, v88, 32
	v_readlane_b32 s51, v88, 48
	s_nop 1
	v_mov_b32_e32 v88, s48
	v_add_f32_e32 v88, s49, v88
	v_add_f32_e32 v88, s50, v88
	v_add_f32_e32 v88, s51, v88
	v_fmamk_f32 v88, v88, 0x3a800000, v16
	v_mul_f32_e32 v89, 0x4b800000, v88
	v_cmp_gt_f32_e64 s[8:9], s3, v88
	s_nop 1
	v_cndmask_b32_e64 v88, v88, v89, s[8:9]
	v_rsq_f32_e32 v88, v88
	s_nop 0
	v_mul_f32_e32 v89, 0x45800000, v88
	v_cndmask_b32_e64 v88, v88, v89, s[8:9]
	v_mul_f32_e32 v32, v32, v88
	v_mul_f32_e32 v33, v33, v88
	v_mul_f32_e32 v34, v34, v88
	v_mul_f32_e32 v35, v35, v88
	v_mul_f32_e32 v36, v36, v88
	v_mul_f32_e32 v37, v37, v88
	v_mul_f32_e32 v38, v38, v88
	v_mul_f32_e32 v39, v39, v88
	v_mul_f32_e32 v40, v40, v88
	v_mul_f32_e32 v41, v41, v88
	v_mul_f32_e32 v42, v42, v88
	v_mul_f32_e32 v43, v43, v88
	v_mul_f32_e32 v44, v44, v88
	v_mul_f32_e32 v45, v45, v88
	v_mul_f32_e32 v46, v46, v88
	v_mul_f32_e32 v47, v47, v88
	v_mul_f32_e32 v32, v0, v32
	v_mul_f32_e32 v33, v1, v33
	v_mul_f32_e32 v34, v2, v34
	v_mul_f32_e32 v35, v3, v35
	v_mul_f32_e32 v36, v4, v36
	v_mul_f32_e32 v37, v5, v37
	v_mul_f32_e32 v38, v6, v38
	v_mul_f32_e32 v39, v7, v39
	v_mul_f32_e32 v40, v8, v40
	v_mul_f32_e32 v41, v9, v41
	v_mul_f32_e32 v42, v10, v42
	v_mul_f32_e32 v43, v11, v43
	v_mul_f32_e32 v44, v12, v44
	v_mul_f32_e32 v45, v13, v45
	v_mul_f32_e32 v46, v14, v46
	v_mul_f32_e32 v47, v15, v47
	s_add_i32 s7, s42, 0
	v_add_u32_e32 v18, s7, v17
	ds_write_b128 v18, v[32:35]
	ds_write_b128 v18, v[36:39] offset:1024
	ds_write_b128 v18, v[40:43] offset:2048
	ds_write_b128 v18, v[44:47] offset:3072
	v_cvt_pk_bf16_f32 v80, v32, v33
	v_cvt_pk_bf16_f32 v81, v34, v35
	v_cvt_pk_bf16_f32 v82, v36, v37
	v_cvt_pk_bf16_f32 v83, v38, v39
	v_cvt_pk_bf16_f32 v84, v40, v41
	v_cvt_pk_bf16_f32 v85, v42, v43
	v_cvt_pk_bf16_f32 v86, v44, v45
	v_cvt_pk_bf16_f32 v87, v46, v47
	global_store_dwordx2 v29, v[80:81], s[40:41]
	global_store_dwordx2 v29, v[82:83], s[40:41] offset:512
	global_store_dwordx2 v29, v[84:85], s[40:41] offset:1024
	global_store_dwordx2 v29, v[86:87], s[40:41] offset:1536
	v_mul_f32_e32 v64, v48, v48
	v_fmac_f32_e32 v64, v49, v49
	v_mul_f32_e32 v65, v50, v50
	v_fmac_f32_e32 v65, v51, v51
	v_add_f32_e32 v64, v64, v65
	v_mul_f32_e32 v66, v52, v52
	v_fmac_f32_e32 v66, v53, v53
	v_mul_f32_e32 v67, v54, v54
	v_fmac_f32_e32 v67, v55, v55
	v_add_f32_e32 v66, v66, v67
	v_mul_f32_e32 v68, v56, v56
	v_fmac_f32_e32 v68, v57, v57
	v_mul_f32_e32 v69, v58, v58
	v_fmac_f32_e32 v69, v59, v59
	v_add_f32_e32 v68, v68, v69
	v_mul_f32_e32 v70, v60, v60
	v_fmac_f32_e32 v70, v61, v61
	v_mul_f32_e32 v71, v62, v62
	v_fmac_f32_e32 v71, v63, v63
	v_add_f32_e32 v70, v70, v71
	v_add_f32_e32 v64, v64, v66
	v_add_f32_e32 v64, v64, v68
	v_add_f32_e32 v64, v64, v70
	s_nop 1
	v_add_f32_dpp v88, v64, v64 quad_perm:[1,0,3,2] row_mask:0xf bank_mask:0xf
	s_nop 1
	v_add_f32_dpp v88, v88, v88 quad_perm:[2,3,0,1] row_mask:0xf bank_mask:0xf
	s_nop 1
	v_add_f32_dpp v88, v88, v88 row_half_mirror row_mask:0xf bank_mask:0xf
	s_nop 1
	v_add_f32_dpp v88, v88, v88 row_mirror row_mask:0xf bank_mask:0xf
	s_nop 1
	v_readlane_b32 s48, v88, 0
	v_readlane_b32 s49, v88, 16
	v_readlane_b32 s50, v88, 32
	v_readlane_b32 s51, v88, 48
	s_nop 1
	v_mov_b32_e32 v88, s48
	v_add_f32_e32 v88, s49, v88
	v_add_f32_e32 v88, s50, v88
	v_add_f32_e32 v88, s51, v88
	v_fmamk_f32 v88, v88, 0x3a800000, v16
	v_mul_f32_e32 v89, 0x4b800000, v88
	v_cmp_gt_f32_e64 s[8:9], s3, v88
	s_nop 1
	v_cndmask_b32_e64 v88, v88, v89, s[8:9]
	v_rsq_f32_e32 v88, v88
	s_nop 0
	v_mul_f32_e32 v89, 0x45800000, v88
	v_cndmask_b32_e64 v88, v88, v89, s[8:9]
	v_mul_f32_e32 v48, v48, v88
	v_mul_f32_e32 v49, v49, v88
	v_mul_f32_e32 v50, v50, v88
	v_mul_f32_e32 v51, v51, v88
	v_mul_f32_e32 v52, v52, v88
	v_mul_f32_e32 v53, v53, v88
	v_mul_f32_e32 v54, v54, v88
	v_mul_f32_e32 v55, v55, v88
	v_mul_f32_e32 v56, v56, v88
	v_mul_f32_e32 v57, v57, v88
	v_mul_f32_e32 v58, v58, v88
	v_mul_f32_e32 v59, v59, v88
	v_mul_f32_e32 v60, v60, v88
	v_mul_f32_e32 v61, v61, v88
	v_mul_f32_e32 v62, v62, v88
	v_mul_f32_e32 v63, v63, v88
	v_mul_f32_e32 v48, v0, v48
	v_mul_f32_e32 v49, v1, v49
	v_mul_f32_e32 v50, v2, v50
	v_mul_f32_e32 v51, v3, v51
	v_mul_f32_e32 v52, v4, v52
	v_mul_f32_e32 v53, v5, v53
	v_mul_f32_e32 v54, v6, v54
	v_mul_f32_e32 v55, v7, v55
	v_mul_f32_e32 v56, v8, v56
	v_mul_f32_e32 v57, v9, v57
	v_mul_f32_e32 v58, v10, v58
	v_mul_f32_e32 v59, v11, v59
	v_mul_f32_e32 v60, v12, v60
	v_mul_f32_e32 v61, v13, v61
	v_mul_f32_e32 v62, v14, v62
	v_mul_f32_e32 v63, v15, v63
	s_add_i32 s7, s42, 32896
	v_add_u32_e32 v18, s7, v17
	ds_write_b128 v18, v[48:51]
	ds_write_b128 v18, v[52:55] offset:1024
	ds_write_b128 v18, v[56:59] offset:2048
	ds_write_b128 v18, v[60:63] offset:3072
	s_add_u32 s10, s40, 0x400000
	s_addc_u32 s11, s41, 0
	v_cvt_pk_bf16_f32 v80, v48, v49
	v_cvt_pk_bf16_f32 v81, v50, v51
	v_cvt_pk_bf16_f32 v82, v52, v53
	v_cvt_pk_bf16_f32 v83, v54, v55
	v_cvt_pk_bf16_f32 v84, v56, v57
	v_cvt_pk_bf16_f32 v85, v58, v59
	v_cvt_pk_bf16_f32 v86, v60, v61
	v_cvt_pk_bf16_f32 v87, v62, v63
	global_store_dwordx2 v29, v[80:81], s[10:11]
	global_store_dwordx2 v29, v[82:83], s[10:11] offset:512
	global_store_dwordx2 v29, v[84:85], s[10:11] offset:1024
	global_store_dwordx2 v29, v[86:87], s[10:11] offset:1536
	s_add_u32 s40, s40, 0x800000
	s_addc_u32 s41, s41, 0
	s_waitcnt lgkmcnt(0)
	s_barrier
; #define LAS __attribute__((address_space(3)))
; __device__ __forceinline__ float wave_sum(float v) { for (int o = 32; o >= 1; o >>= 1) v += __shfl_xor(v, o); return v; }
; __device__ __forceinline__ void p0_rows(const Args& a, LAS unsigned char* lds, int gw, int NGW, int wave, int lane, int tid) {
;     ...
;         const f32x4* xr = (const f32x4*)xrow_ptr(a, row) + lane; f32x4 v[4]; float s = 0.f;
; #pragma unroll
;         for (int j = 0; j < 4; ++j) { v[j] = xr[64 * j]; s += (v[j][0] * v[j][0] + v[j][1] * v[j][1]) + (v[j][2] * v[j][2] + v[j][3] * v[j][3]); }
;         const float rstd = rsqrtf(wave_sum(s) * (1.f / DM) + EPS);
;     ...
;         const int jj = lane & 15, p = lane >> 4; float acc = 0.f;
;         const LAS float* hp = hrow + p * 264; const LAS float* wp = WdL + p * 4112 + jj;
; #pragma unroll 8
;         for (int kk = 0; kk < 256; ++kk) acc += hp[kk] * wp[kk * 16];
;         acc += __shfl_xor(acc, 16); acc += __shfl_xor(acc, 32);
;         if (lane < 16) DLR[(size_t)row * 16 + jj] = acc;
	s_waitcnt vmcnt(16)
	ds_read_b128 v[128:131], v19
	ds_read_b128 v[132:135], v19 offset:16
	ds_read_b128 v[136:139], v19 offset:32
	ds_read_b128 v[140:143], v19 offset:48
	ds_read_b128 v[144:147], v19 offset:64
	ds_read_b128 v[148:151], v19 offset:80
	ds_read_b128 v[152:155], v19 offset:96
	ds_read_b128 v[156:159], v19 offset:112
	s_waitcnt lgkmcnt(7)
	v_mfma_f32_16x16x4_f32 v[160:163], v128, v96, 0
	v_mfma_f32_16x16x4_f32 v[164:167], v129, v97, 0
	v_mfma_f32_16x16x4_f32 v[160:163], v130, v98, v[160:163]
	v_mfma_f32_16x16x4_f32 v[164:167], v131, v99, v[164:167]
	s_waitcnt lgkmcnt(6)
	v_mfma_f32_16x16x4_f32 v[160:163], v132, v100, v[160:163]
	v_mfma_f32_16x16x4_f32 v[164:167], v133, v101, v[164:167]
	v_mfma_f32_16x16x4_f32 v[160:163], v134, v102, v[160:163]
	v_mfma_f32_16x16x4_f32 v[164:167], v135, v103, v[164:167]
	s_waitcnt lgkmcnt(5)
	v_mfma_f32_16x16x4_f32 v[160:163], v136, v104, v[160:163]
	v_mfma_f32_16x16x4_f32 v[164:167], v137, v105, v[164:167]
	v_mfma_f32_16x16x4_f32 v[160:163], v138, v106, v[160:163]
	v_mfma_f32_16x16x4_f32 v[164:167], v139, v107, v[164:167]
	s_waitcnt lgkmcnt(4)
	v_mfma_f32_16x16x4_f32 v[160:163], v140, v108, v[160:163]
	v_mfma_f32_16x16x4_f32 v[164:167], v141, v109, v[164:167]
	v_mfma_f32_16x16x4_f32 v[160:163], v142, v110, v[160:163]
	v_mfma_f32_16x16x4_f32 v[164:167], v143, v111, v[164:167]
	s_waitcnt lgkmcnt(3)
	v_mfma_f32_16x16x4_f32 v[160:163], v144, v112, v[160:163]
	v_mfma_f32_16x16x4_f32 v[164:167], v145, v113, v[164:167]
	v_mfma_f32_16x16x4_f32 v[160:163], v146, v114, v[160:163]
	v_mfma_f32_16x16x4_f32 v[164:167], v147, v115, v[164:167]
	s_waitcnt lgkmcnt(2)
	v_mfma_f32_16x16x4_f32 v[160:163], v148, v116, v[160:163]
	v_mfma_f32_16x16x4_f32 v[164:167], v149, v117, v[164:167]
	v_mfma_f32_16x16x4_f32 v[160:163], v150, v118, v[160:163]
	v_mfma_f32_16x16x4_f32 v[164:167], v151, v119, v[164:167]
	s_waitcnt lgkmcnt(1)
	v_mfma_f32_16x16x4_f32 v[160:163], v152, v120, v[160:163]
	v_mfma_f32_16x16x4_f32 v[164:167], v153, v121, v[164:167]
	v_mfma_f32_16x16x4_f32 v[160:163], v154, v122, v[160:163]
	v_mfma_f32_16x16x4_f32 v[164:167], v155, v123, v[164:167]
	s_waitcnt lgkmcnt(0)
	v_mfma_f32_16x16x4_f32 v[160:163], v156, v124, v[160:163]
	v_mfma_f32_16x16x4_f32 v[164:167], v157, v125, v[164:167]
	v_mfma_f32_16x16x4_f32 v[160:163], v158, v126, v[160:163]
	v_mfma_f32_16x16x4_f32 v[164:167], v159, v127, v[164:167]
	s_nop 9
	v_add_f32_e32 v160, v160, v164
	v_add_f32_e32 v161, v161, v165
	v_add_f32_e32 v162, v162, v166
	v_add_f32_e32 v163, v163, v167
	ds_write_b128 v21, v[160:163]
	s_waitcnt lgkmcnt(0)
	s_barrier
	s_cmp_lt_u32 s93, 4
	s_cbranch_scc0 .Lp0m_s3skip_b0
	ds_read_b32 v168, v22
	ds_read_b32 v169, v22 offset:1024
	ds_read_b32 v170, v22 offset:2048
	ds_read_b32 v171, v22 offset:3072
	ds_read_b32 v172, v22 offset:4096
	ds_read_b32 v173, v22 offset:5120
	ds_read_b32 v174, v22 offset:6144
	ds_read_b32 v175, v22 offset:7168
	s_waitcnt lgkmcnt(6)
	v_add_f32_e32 v168, v168, v169
	s_waitcnt lgkmcnt(5)
	v_add_f32_e32 v168, v168, v170
	s_waitcnt lgkmcnt(4)
	v_add_f32_e32 v168, v168, v171
	s_waitcnt lgkmcnt(3)
	v_add_f32_e32 v168, v168, v172
	s_waitcnt lgkmcnt(2)
	v_add_f32_e32 v168, v168, v173
	s_waitcnt lgkmcnt(1)
	v_add_f32_e32 v168, v168, v174
	s_waitcnt lgkmcnt(0)
	v_add_f32_e32 v168, v168, v175
	global_store_dword v23, v168, s[52:53]
.Lp0m_s3skip_b0:
	v_add_u32_e32 v23, 0x40000, v23
	s_add_u32 s44, s44, 0x1000000
	s_addc_u32 s45, s45, 0
	global_load_dwordx4 v[32:35], v28, s[44:45]
	global_load_dwordx4 v[36:39], v28, s[44:45] offset:1024
	global_load_dwordx4 v[40:43], v28, s[44:45] offset:2048
	global_load_dwordx4 v[44:47], v28, s[44:45] offset:3072
	s_add_u32 s10, s44, 0x800000
	s_addc_u32 s11, s45, 0
	global_load_dwordx4 v[48:51], v28, s[10:11]
	global_load_dwordx4 v[52:55], v28, s[10:11] offset:1024
	global_load_dwordx4 v[56:59], v28, s[10:11] offset:2048
	global_load_dwordx4 v[60:63], v28, s[10:11] offset:3072
	s_waitcnt vmcnt(16)
	v_mul_f32_e32 v64, v192, v192
	v_fmac_f32_e32 v64, v193, v193
	v_mul_f32_e32 v65, v194, v194
	v_fmac_f32_e32 v65, v195, v195
	v_add_f32_e32 v64, v64, v65
	v_mul_f32_e32 v66, v196, v196
	v_fmac_f32_e32 v66, v197, v197
	v_mul_f32_e32 v67, v198, v198
	v_fmac_f32_e32 v67, v199, v199
	v_add_f32_e32 v66, v66, v67
	v_mul_f32_e32 v68, v200, v200
	v_fmac_f32_e32 v68, v201, v201
	v_mul_f32_e32 v69, v202, v202
	v_fmac_f32_e32 v69, v203, v203
	v_add_f32_e32 v68, v68, v69
	v_mul_f32_e32 v70, v204, v204
	v_fmac_f32_e32 v70, v205, v205
	v_mul_f32_e32 v71, v206, v206
	v_fmac_f32_e32 v71, v207, v207
	v_add_f32_e32 v70, v70, v71
	v_add_f32_e32 v64, v64, v66
	v_add_f32_e32 v64, v64, v68
	v_add_f32_e32 v64, v64, v70
	s_nop 1
	v_add_f32_dpp v88, v64, v64 quad_perm:[1,0,3,2] row_mask:0xf bank_mask:0xf
	s_nop 1
	v_add_f32_dpp v88, v88, v88 quad_perm:[2,3,0,1] row_mask:0xf bank_mask:0xf
	s_nop 1
	v_add_f32_dpp v88, v88, v88 row_half_mirror row_mask:0xf bank_mask:0xf
	s_nop 1
	v_add_f32_dpp v88, v88, v88 row_mirror row_mask:0xf bank_mask:0xf
	s_nop 1
	v_readlane_b32 s48, v88, 0
	v_readlane_b32 s49, v88, 16
	v_readlane_b32 s50, v88, 32
	v_readlane_b32 s51, v88, 48
	s_nop 1
	v_mov_b32_e32 v88, s48
	v_add_f32_e32 v88, s49, v88
	v_add_f32_e32 v88, s50, v88
	v_add_f32_e32 v88, s51, v88
	v_fmamk_f32 v88, v88, 0x3a800000, v16
	v_mul_f32_e32 v89, 0x4b800000, v88
	v_cmp_gt_f32_e64 s[8:9], s3, v88
	s_nop 1
	v_cndmask_b32_e64 v88, v88, v89, s[8:9]
	v_rsq_f32_e32 v88, v88
	s_nop 0
	v_mul_f32_e32 v89, 0x45800000, v88
	v_cndmask_b32_e64 v88, v88, v89, s[8:9]
	v_mul_f32_e32 v192, v192, v88
	v_mul_f32_e32 v193, v193, v88
	v_mul_f32_e32 v194, v194, v88
	v_mul_f32_e32 v195, v195, v88
	v_mul_f32_e32 v196, v196, v88
; #define LAS __attribute__((address_space(3)))
; __device__ __forceinline__ void wave_lds_sync() { asm volatile("s_waitcnt lgkmcnt(0)" ::: "memory"); __builtin_amdgcn_wave_barrier(); }
; __device__ __forceinline__ u32x2 pk4(f32x4 v) { u32x2 w; w.x = cvt_pk_bf16(v[0], v[1]); w.y = cvt_pk_bf16(v[2], v[3]); return w; }
; __device__ __forceinline__ void p0_rows(const Args& a, LAS unsigned char* lds, int gw, int NGW, int wave, int lane, int tid) {
;     ...
;         u32x2* ho = (u32x2*)(H + (size_t)row * DM) + lane;
; #pragma unroll
;         for (int j = 0; j < 4; ++j) { v[j] = v[j] * rstd * g[j]; ho[64 * j] = pk4(v[j]); *(LAS f32x4*)(hrow + j * 264 + 4 * lane) = v[j]; }
;         wave_lds_sync();
	v_mul_f32_e32 v197, v197, v88
	v_mul_f32_e32 v198, v198, v88
	v_mul_f32_e32 v199, v199, v88
	v_mul_f32_e32 v200, v200, v88
	v_mul_f32_e32 v201, v201, v88
	v_mul_f32_e32 v202, v202, v88
	v_mul_f32_e32 v203, v203, v88
	v_mul_f32_e32 v204, v204, v88
	v_mul_f32_e32 v205, v205, v88
	v_mul_f32_e32 v206, v206, v88
	v_mul_f32_e32 v207, v207, v88
	v_mul_f32_e32 v192, v0, v192
	v_mul_f32_e32 v193, v1, v193
	v_mul_f32_e32 v194, v2, v194
	v_mul_f32_e32 v195, v3, v195
	v_mul_f32_e32 v196, v4, v196
	v_mul_f32_e32 v197, v5, v197
	v_mul_f32_e32 v198, v6, v198
	v_mul_f32_e32 v199, v7, v199
	v_mul_f32_e32 v200, v8, v200
	v_mul_f32_e32 v201, v9, v201
	v_mul_f32_e32 v202, v10, v202
	v_mul_f32_e32 v203, v11, v203
	v_mul_f32_e32 v204, v12, v204
	v_mul_f32_e32 v205, v13, v205
	v_mul_f32_e32 v206, v14, v206
	v_mul_f32_e32 v207, v15, v207
	s_add_i32 s7, s42, 65792
	v_add_u32_e32 v18, s7, v17
	ds_write_b128 v18, v[192:195]
	ds_write_b128 v18, v[196:199] offset:1024
	ds_write_b128 v18, v[200:203] offset:2048
	ds_write_b128 v18, v[204:207] offset:3072
	v_cvt_pk_bf16_f32 v80, v192, v193
	v_cvt_pk_bf16_f32 v81, v194, v195
	v_cvt_pk_bf16_f32 v82, v196, v197
	v_cvt_pk_bf16_f32 v83, v198, v199
	v_cvt_pk_bf16_f32 v84, v200, v201
	v_cvt_pk_bf16_f32 v85, v202, v203
	v_cvt_pk_bf16_f32 v86, v204, v205
	v_cvt_pk_bf16_f32 v87, v206, v207
	global_store_dwordx2 v29, v[80:81], s[40:41]
	global_store_dwordx2 v29, v[82:83], s[40:41] offset:512
	global_store_dwordx2 v29, v[84:85], s[40:41] offset:1024
	global_store_dwordx2 v29, v[86:87], s[40:41] offset:1536
	v_mul_f32_e32 v64, v208, v208
	v_fmac_f32_e32 v64, v209, v209
	v_mul_f32_e32 v65, v210, v210
	v_fmac_f32_e32 v65, v211, v211
	v_add_f32_e32 v64, v64, v65
	v_mul_f32_e32 v66, v212, v212
	v_fmac_f32_e32 v66, v213, v213
	v_mul_f32_e32 v67, v214, v214
	v_fmac_f32_e32 v67, v215, v215
	v_add_f32_e32 v66, v66, v67
	v_mul_f32_e32 v68, v216, v216
	v_fmac_f32_e32 v68, v217, v217
	v_mul_f32_e32 v69, v218, v218
	v_fmac_f32_e32 v69, v219, v219
	v_add_f32_e32 v68, v68, v69
	v_mul_f32_e32 v70, v220, v220
	v_fmac_f32_e32 v70, v221, v221
	v_mul_f32_e32 v71, v222, v222
	v_fmac_f32_e32 v71, v223, v223
	v_add_f32_e32 v70, v70, v71
	v_add_f32_e32 v64, v64, v66
	v_add_f32_e32 v64, v64, v68
	v_add_f32_e32 v64, v64, v70
	s_nop 1
	v_add_f32_dpp v88, v64, v64 quad_perm:[1,0,3,2] row_mask:0xf bank_mask:0xf
	s_nop 1
	v_add_f32_dpp v88, v88, v88 quad_perm:[2,3,0,1] row_mask:0xf bank_mask:0xf
	s_nop 1
	v_add_f32_dpp v88, v88, v88 row_half_mirror row_mask:0xf bank_mask:0xf
	s_nop 1
	v_add_f32_dpp v88, v88, v88 row_mirror row_mask:0xf bank_mask:0xf
	s_nop 1
	v_readlane_b32 s48, v88, 0
	v_readlane_b32 s49, v88, 16
	v_readlane_b32 s50, v88, 32
	v_readlane_b32 s51, v88, 48
	s_nop 1
	v_mov_b32_e32 v88, s48
	v_add_f32_e32 v88, s49, v88
	v_add_f32_e32 v88, s50, v88
	v_add_f32_e32 v88, s51, v88
	v_fmamk_f32 v88, v88, 0x3a800000, v16
	v_mul_f32_e32 v89, 0x4b800000, v88
	v_cmp_gt_f32_e64 s[8:9], s3, v88
	s_nop 1
	v_cndmask_b32_e64 v88, v88, v89, s[8:9]
	v_rsq_f32_e32 v88, v88
	s_nop 0
	v_mul_f32_e32 v89, 0x45800000, v88
	v_cndmask_b32_e64 v88, v88, v89, s[8:9]
	v_mul_f32_e32 v208, v208, v88
	v_mul_f32_e32 v209, v209, v88
	v_mul_f32_e32 v210, v210, v88
	v_mul_f32_e32 v211, v211, v88
	v_mul_f32_e32 v212, v212, v88
	v_mul_f32_e32 v213, v213, v88
	v_mul_f32_e32 v214, v214, v88
	v_mul_f32_e32 v215, v215, v88
	v_mul_f32_e32 v216, v216, v88
	v_mul_f32_e32 v217, v217, v88
	v_mul_f32_e32 v218, v218, v88
	v_mul_f32_e32 v219, v219, v88
	v_mul_f32_e32 v220, v220, v88
	v_mul_f32_e32 v221, v221, v88
	v_mul_f32_e32 v222, v222, v88
	v_mul_f32_e32 v223, v223, v88
	v_mul_f32_e32 v208, v0, v208
	v_mul_f32_e32 v209, v1, v209
	v_mul_f32_e32 v210, v2, v210
	v_mul_f32_e32 v211, v3, v211
	v_mul_f32_e32 v212, v4, v212
	v_mul_f32_e32 v213, v5, v213
	v_mul_f32_e32 v214, v6, v214
	v_mul_f32_e32 v215, v7, v215
	v_mul_f32_e32 v216, v8, v216
	v_mul_f32_e32 v217, v9, v217
	v_mul_f32_e32 v218, v10, v218
	v_mul_f32_e32 v219, v11, v219
	v_mul_f32_e32 v220, v12, v220
	v_mul_f32_e32 v221, v13, v221
	v_mul_f32_e32 v222, v14, v222
	v_mul_f32_e32 v223, v15, v223
	s_add_i32 s7, s42, 98688
	v_add_u32_e32 v18, s7, v17
	ds_write_b128 v18, v[208:211]
	ds_write_b128 v18, v[212:215] offset:1024
	ds_write_b128 v18, v[216:219] offset:2048
	ds_write_b128 v18, v[220:223] offset:3072
	s_add_u32 s10, s40, 0x400000
	s_addc_u32 s11, s41, 0
	v_cvt_pk_bf16_f32 v80, v208, v209
	v_cvt_pk_bf16_f32 v81, v210, v211
	v_cvt_pk_bf16_f32 v82, v212, v213
	v_cvt_pk_bf16_f32 v83, v214, v215
	v_cvt_pk_bf16_f32 v84, v216, v217
	v_cvt_pk_bf16_f32 v85, v218, v219
	v_cvt_pk_bf16_f32 v86, v220, v221
	v_cvt_pk_bf16_f32 v87, v222, v223
	global_store_dwordx2 v29, v[80:81], s[10:11]
	global_store_dwordx2 v29, v[82:83], s[10:11] offset:512
	global_store_dwordx2 v29, v[84:85], s[10:11] offset:1024
	global_store_dwordx2 v29, v[86:87], s[10:11] offset:1536
	s_add_u32 s40, s40, 0x800000
	s_addc_u32 s41, s41, 0
	s_waitcnt lgkmcnt(0)
	s_barrier
; #define LAS __attribute__((address_space(3)))
; __device__ __forceinline__ float wave_sum(float v) { for (int o = 32; o >= 1; o >>= 1) v += __shfl_xor(v, o); return v; }
; __device__ __forceinline__ void p0_rows(const Args& a, LAS unsigned char* lds, int gw, int NGW, int wave, int lane, int tid) {
;     ...
;         const f32x4* xr = (const f32x4*)xrow_ptr(a, row) + lane; f32x4 v[4]; float s = 0.f;
; #pragma unroll
;         for (int j = 0; j < 4; ++j) { v[j] = xr[64 * j]; s += (v[j][0] * v[j][0] + v[j][1] * v[j][1]) + (v[j][2] * v[j][2] + v[j][3] * v[j][3]); }
;         const float rstd = rsqrtf(wave_sum(s) * (1.f / DM) + EPS);
;     ...
;         const int jj = lane & 15, p = lane >> 4; float acc = 0.f;
;         const LAS float* hp = hrow + p * 264; const LAS float* wp = WdL + p * 4112 + jj;
; #pragma unroll 8
;         for (int kk = 0; kk < 256; ++kk) acc += hp[kk] * wp[kk * 16];
;         acc += __shfl_xor(acc, 16); acc += __shfl_xor(acc, 32);
;         if (lane < 16) DLR[(size_t)row * 16 + jj] = acc;
	ds_read_b128 v[128:131], v20
	ds_read_b128 v[132:135], v20 offset:16
	ds_read_b128 v[136:139], v20 offset:32
	ds_read_b128 v[140:143], v20 offset:48
	ds_read_b128 v[144:147], v20 offset:64
	ds_read_b128 v[148:151], v20 offset:80
	ds_read_b128 v[152:155], v20 offset:96
	ds_read_b128 v[156:159], v20 offset:112
	s_waitcnt lgkmcnt(7)
	v_mfma_f32_16x16x4_f32 v[160:163], v128, v96, 0
	v_mfma_f32_16x16x4_f32 v[164:167], v129, v97, 0
	v_mfma_f32_16x16x4_f32 v[160:163], v130, v98, v[160:163]
	v_mfma_f32_16x16x4_f32 v[164:167], v131, v99, v[164:167]
	s_waitcnt lgkmcnt(6)
	v_mfma_f32_16x16x4_f32 v[160:163], v132, v100, v[160:163]
	v_mfma_f32_16x16x4_f32 v[164:167], v133, v101, v[164:167]
	v_mfma_f32_16x16x4_f32 v[160:163], v134, v102, v[160:163]
	v_mfma_f32_16x16x4_f32 v[164:167], v135, v103, v[164:167]
	s_waitcnt lgkmcnt(5)
	v_mfma_f32_16x16x4_f32 v[160:163], v136, v104, v[160:163]
	v_mfma_f32_16x16x4_f32 v[164:167], v137, v105, v[164:167]
	v_mfma_f32_16x16x4_f32 v[160:163], v138, v106, v[160:163]
	v_mfma_f32_16x16x4_f32 v[164:167], v139, v107, v[164:167]
	s_waitcnt lgkmcnt(4)
	v_mfma_f32_16x16x4_f32 v[160:163], v140, v108, v[160:163]
	v_mfma_f32_16x16x4_f32 v[164:167], v141, v109, v[164:167]
	v_mfma_f32_16x16x4_f32 v[160:163], v142, v110, v[160:163]
	v_mfma_f32_16x16x4_f32 v[164:167], v143, v111, v[164:167]
	s_waitcnt lgkmcnt(3)
	v_mfma_f32_16x16x4_f32 v[160:163], v144, v112, v[160:163]
	v_mfma_f32_16x16x4_f32 v[164:167], v145, v113, v[164:167]
	v_mfma_f32_16x16x4_f32 v[160:163], v146, v114, v[160:163]
	v_mfma_f32_16x16x4_f32 v[164:167], v147, v115, v[164:167]
	s_waitcnt lgkmcnt(2)
	v_mfma_f32_16x16x4_f32 v[160:163], v148, v116, v[160:163]
	v_mfma_f32_16x16x4_f32 v[164:167], v149, v117, v[164:167]
	v_mfma_f32_16x16x4_f32 v[160:163], v150, v118, v[160:163]
	v_mfma_f32_16x16x4_f32 v[164:167], v151, v119, v[164:167]
	s_waitcnt lgkmcnt(1)
	v_mfma_f32_16x16x4_f32 v[160:163], v152, v120, v[160:163]
	v_mfma_f32_16x16x4_f32 v[164:167], v153, v121, v[164:167]
	v_mfma_f32_16x16x4_f32 v[160:163], v154, v122, v[160:163]
	v_mfma_f32_16x16x4_f32 v[164:167], v155, v123, v[164:167]
	s_waitcnt lgkmcnt(0)
	v_mfma_f32_16x16x4_f32 v[160:163], v156, v124, v[160:163]
	v_mfma_f32_16x16x4_f32 v[164:167], v157, v125, v[164:167]
	v_mfma_f32_16x16x4_f32 v[160:163], v158, v126, v[160:163]
	v_mfma_f32_16x16x4_f32 v[164:167], v159, v127, v[164:167]
	s_nop 9
	v_add_f32_e32 v160, v160, v164
	v_add_f32_e32 v161, v161, v165
	v_add_f32_e32 v162, v162, v166
	v_add_f32_e32 v163, v163, v167
	ds_write_b128 v21, v[160:163]
	s_waitcnt lgkmcnt(0)
	s_barrier
	s_cmp_lt_u32 s93, 4
	s_cbranch_scc0 .Lp0m_s3skip_b1
	ds_read_b32 v168, v22
	ds_read_b32 v169, v22 offset:1024
	ds_read_b32 v170, v22 offset:2048
	ds_read_b32 v171, v22 offset:3072
	ds_read_b32 v172, v22 offset:4096
	ds_read_b32 v173, v22 offset:5120
	ds_read_b32 v174, v22 offset:6144
	ds_read_b32 v175, v22 offset:7168
	s_waitcnt lgkmcnt(6)
	v_add_f32_e32 v168, v168, v169
	s_waitcnt lgkmcnt(5)
	v_add_f32_e32 v168, v168, v170
	s_waitcnt lgkmcnt(4)
	v_add_f32_e32 v168, v168, v171
	s_waitcnt lgkmcnt(3)
	v_add_f32_e32 v168, v168, v172
	s_waitcnt lgkmcnt(2)
	v_add_f32_e32 v168, v168, v173
	s_waitcnt lgkmcnt(1)
	v_add_f32_e32 v168, v168, v174
	s_waitcnt lgkmcnt(0)
	v_add_f32_e32 v168, v168, v175
	global_store_dword v23, v168, s[52:53]
.Lp0m_s3skip_b1:
	v_add_u32_e32 v23, 0x40000, v23
	s_add_u32 s44, s44, 0x1000000
	s_addc_u32 s45, s45, 0
	global_load_dwordx4 v[192:195], v28, s[44:45]
	global_load_dwordx4 v[196:199], v28, s[44:45] offset:1024
	global_load_dwordx4 v[200:203], v28, s[44:45] offset:2048
	global_load_dwordx4 v[204:207], v28, s[44:45] offset:3072
	s_add_u32 s10, s44, 0x800000
	s_addc_u32 s11, s45, 0
	global_load_dwordx4 v[208:211], v28, s[10:11]
	global_load_dwordx4 v[212:215], v28, s[10:11] offset:1024
	global_load_dwordx4 v[216:219], v28, s[10:11] offset:2048
	global_load_dwordx4 v[220:223], v28, s[10:11] offset:3072
	s_waitcnt vmcnt(16)
	v_mul_f32_e32 v64, v32, v32
	v_fmac_f32_e32 v64, v33, v33
	v_mul_f32_e32 v65, v34, v34
	v_fmac_f32_e32 v65, v35, v35
	v_add_f32_e32 v64, v64, v65
	v_mul_f32_e32 v66, v36, v36
	v_fmac_f32_e32 v66, v37, v37
	v_mul_f32_e32 v67, v38, v38
	v_fmac_f32_e32 v67, v39, v39
	v_add_f32_e32 v66, v66, v67
	v_mul_f32_e32 v68, v40, v40
	v_fmac_f32_e32 v68, v41, v41
	v_mul_f32_e32 v69, v42, v42
	v_fmac_f32_e32 v69, v43, v43
	v_add_f32_e32 v68, v68, v69
	v_mul_f32_e32 v70, v44, v44
	v_fmac_f32_e32 v70, v45, v45
	v_mul_f32_e32 v71, v46, v46
	v_fmac_f32_e32 v71, v47, v47
	v_add_f32_e32 v70, v70, v71
	v_add_f32_e32 v64, v64, v66
	v_add_f32_e32 v64, v64, v68
	v_add_f32_e32 v64, v64, v70
	s_nop 1
	v_add_f32_dpp v88, v64, v64 quad_perm:[1,0,3,2] row_mask:0xf bank_mask:0xf
	s_nop 1
	v_add_f32_dpp v88, v88, v88 quad_perm:[2,3,0,1] row_mask:0xf bank_mask:0xf
	s_nop 1
	v_add_f32_dpp v88, v88, v88 row_half_mirror row_mask:0xf bank_mask:0xf
	s_nop 1
	v_add_f32_dpp v88, v88, v88 row_mirror row_mask:0xf bank_mask:0xf
	s_nop 1
	v_readlane_b32 s48, v88, 0
	v_readlane_b32 s49, v88, 16
	v_readlane_b32 s50, v88, 32
	v_readlane_b32 s51, v88, 48
	s_nop 1
	v_mov_b32_e32 v88, s48
	v_add_f32_e32 v88, s49, v88
	v_add_f32_e32 v88, s50, v88
	v_add_f32_e32 v88, s51, v88
	v_fmamk_f32 v88, v88, 0x3a800000, v16
	v_mul_f32_e32 v89, 0x4b800000, v88
	v_cmp_gt_f32_e64 s[8:9], s3, v88
	s_nop 1
	v_cndmask_b32_e64 v88, v88, v89, s[8:9]
	v_rsq_f32_e32 v88, v88
	s_nop 0
	v_mul_f32_e32 v89, 0x45800000, v88
	v_cndmask_b32_e64 v88, v88, v89, s[8:9]
	v_mul_f32_e32 v32, v32, v88
	v_mul_f32_e32 v33, v33, v88
	v_mul_f32_e32 v34, v34, v88
	v_mul_f32_e32 v35, v35, v88
	v_mul_f32_e32 v36, v36, v88
	v_mul_f32_e32 v37, v37, v88
	v_mul_f32_e32 v38, v38, v88
; #define LAS __attribute__((address_space(3)))
; __device__ __forceinline__ void wave_lds_sync() { asm volatile("s_waitcnt lgkmcnt(0)" ::: "memory"); __builtin_amdgcn_wave_barrier(); }
; __device__ __forceinline__ u32x2 pk4(f32x4 v) { u32x2 w; w.x = cvt_pk_bf16(v[0], v[1]); w.y = cvt_pk_bf16(v[2], v[3]); return w; }
; __device__ __forceinline__ void p0_rows(const Args& a, LAS unsigned char* lds, int gw, int NGW, int wave, int lane, int tid) {
;     ...
;         u32x2* ho = (u32x2*)(H + (size_t)row * DM) + lane;
; #pragma unroll
;         for (int j = 0; j < 4; ++j) { v[j] = v[j] * rstd * g[j]; ho[64 * j] = pk4(v[j]); *(LAS f32x4*)(hrow + j * 264 + 4 * lane) = v[j]; }
;         wave_lds_sync();
	v_mul_f32_e32 v39, v39, v88
	v_mul_f32_e32 v40, v40, v88
	v_mul_f32_e32 v41, v41, v88
	v_mul_f32_e32 v42, v42, v88
	v_mul_f32_e32 v43, v43, v88
	v_mul_f32_e32 v44, v44, v88
	v_mul_f32_e32 v45, v45, v88
	v_mul_f32_e32 v46, v46, v88
	v_mul_f32_e32 v47, v47, v88
	v_mul_f32_e32 v32, v0, v32
	v_mul_f32_e32 v33, v1, v33
	v_mul_f32_e32 v34, v2, v34
	v_mul_f32_e32 v35, v3, v35
	v_mul_f32_e32 v36, v4, v36
	v_mul_f32_e32 v37, v5, v37
	v_mul_f32_e32 v38, v6, v38
	v_mul_f32_e32 v39, v7, v39
	v_mul_f32_e32 v40, v8, v40
	v_mul_f32_e32 v41, v9, v41
	v_mul_f32_e32 v42, v10, v42
	v_mul_f32_e32 v43, v11, v43
	v_mul_f32_e32 v44, v12, v44
	v_mul_f32_e32 v45, v13, v45
	v_mul_f32_e32 v46, v14, v46
	v_mul_f32_e32 v47, v15, v47
	s_add_i32 s7, s42, 0
	v_add_u32_e32 v18, s7, v17
	ds_write_b128 v18, v[32:35]
	ds_write_b128 v18, v[36:39] offset:1024
	ds_write_b128 v18, v[40:43] offset:2048
	ds_write_b128 v18, v[44:47] offset:3072
	v_cvt_pk_bf16_f32 v80, v32, v33
	v_cvt_pk_bf16_f32 v81, v34, v35
	v_cvt_pk_bf16_f32 v82, v36, v37
	v_cvt_pk_bf16_f32 v83, v38, v39
	v_cvt_pk_bf16_f32 v84, v40, v41
	v_cvt_pk_bf16_f32 v85, v42, v43
	v_cvt_pk_bf16_f32 v86, v44, v45
	v_cvt_pk_bf16_f32 v87, v46, v47
	global_store_dwordx2 v29, v[80:81], s[40:41]
	global_store_dwordx2 v29, v[82:83], s[40:41] offset:512
	global_store_dwordx2 v29, v[84:85], s[40:41] offset:1024
	global_store_dwordx2 v29, v[86:87], s[40:41] offset:1536
	v_mul_f32_e32 v64, v48, v48
	v_fmac_f32_e32 v64, v49, v49
	v_mul_f32_e32 v65, v50, v50
	v_fmac_f32_e32 v65, v51, v51
	v_add_f32_e32 v64, v64, v65
	v_mul_f32_e32 v66, v52, v52
	v_fmac_f32_e32 v66, v53, v53
	v_mul_f32_e32 v67, v54, v54
	v_fmac_f32_e32 v67, v55, v55
	v_add_f32_e32 v66, v66, v67
	v_mul_f32_e32 v68, v56, v56
	v_fmac_f32_e32 v68, v57, v57
	v_mul_f32_e32 v69, v58, v58
	v_fmac_f32_e32 v69, v59, v59
	v_add_f32_e32 v68, v68, v69
	v_mul_f32_e32 v70, v60, v60
	v_fmac_f32_e32 v70, v61, v61
	v_mul_f32_e32 v71, v62, v62
	v_fmac_f32_e32 v71, v63, v63
	v_add_f32_e32 v70, v70, v71
	v_add_f32_e32 v64, v64, v66
	v_add_f32_e32 v64, v64, v68
	v_add_f32_e32 v64, v64, v70
	s_nop 1
	v_add_f32_dpp v88, v64, v64 quad_perm:[1,0,3,2] row_mask:0xf bank_mask:0xf
	s_nop 1
	v_add_f32_dpp v88, v88, v88 quad_perm:[2,3,0,1] row_mask:0xf bank_mask:0xf
	s_nop 1
	v_add_f32_dpp v88, v88, v88 row_half_mirror row_mask:0xf bank_mask:0xf
	s_nop 1
	v_add_f32_dpp v88, v88, v88 row_mirror row_mask:0xf bank_mask:0xf
	s_nop 1
	v_readlane_b32 s48, v88, 0
	v_readlane_b32 s49, v88, 16
	v_readlane_b32 s50, v88, 32
	v_readlane_b32 s51, v88, 48
	s_nop 1
	v_mov_b32_e32 v88, s48
	v_add_f32_e32 v88, s49, v88
	v_add_f32_e32 v88, s50, v88
	v_add_f32_e32 v88, s51, v88
	v_fmamk_f32 v88, v88, 0x3a800000, v16
	v_mul_f32_e32 v89, 0x4b800000, v88
	v_cmp_gt_f32_e64 s[8:9], s3, v88
	s_nop 1
	v_cndmask_b32_e64 v88, v88, v89, s[8:9]
	v_rsq_f32_e32 v88, v88
	s_nop 0
	v_mul_f32_e32 v89, 0x45800000, v88
	v_cndmask_b32_e64 v88, v88, v89, s[8:9]
	v_mul_f32_e32 v48, v48, v88
	v_mul_f32_e32 v49, v49, v88
	v_mul_f32_e32 v50, v50, v88
	v_mul_f32_e32 v51, v51, v88
	v_mul_f32_e32 v52, v52, v88
	v_mul_f32_e32 v53, v53, v88
	v_mul_f32_e32 v54, v54, v88
	v_mul_f32_e32 v55, v55, v88
	v_mul_f32_e32 v56, v56, v88
	v_mul_f32_e32 v57, v57, v88
	v_mul_f32_e32 v58, v58, v88
	v_mul_f32_e32 v59, v59, v88
	v_mul_f32_e32 v60, v60, v88
	v_mul_f32_e32 v61, v61, v88
	v_mul_f32_e32 v62, v62, v88
	v_mul_f32_e32 v63, v63, v88
	v_mul_f32_e32 v48, v0, v48
	v_mul_f32_e32 v49, v1, v49
	v_mul_f32_e32 v50, v2, v50
	v_mul_f32_e32 v51, v3, v51
	v_mul_f32_e32 v52, v4, v52
	v_mul_f32_e32 v53, v5, v53
	v_mul_f32_e32 v54, v6, v54
	v_mul_f32_e32 v55, v7, v55
	v_mul_f32_e32 v56, v8, v56
	v_mul_f32_e32 v57, v9, v57
	v_mul_f32_e32 v58, v10, v58
	v_mul_f32_e32 v59, v11, v59
	v_mul_f32_e32 v60, v12, v60
	v_mul_f32_e32 v61, v13, v61
	v_mul_f32_e32 v62, v14, v62
	v_mul_f32_e32 v63, v15, v63
	s_add_i32 s7, s42, 32896
	v_add_u32_e32 v18, s7, v17
	ds_write_b128 v18, v[48:51]
	ds_write_b128 v18, v[52:55] offset:1024
	ds_write_b128 v18, v[56:59] offset:2048
	ds_write_b128 v18, v[60:63] offset:3072
	s_add_u32 s10, s40, 0x400000
	s_addc_u32 s11, s41, 0
	v_cvt_pk_bf16_f32 v80, v48, v49
	v_cvt_pk_bf16_f32 v81, v50, v51
	v_cvt_pk_bf16_f32 v82, v52, v53
	v_cvt_pk_bf16_f32 v83, v54, v55
	v_cvt_pk_bf16_f32 v84, v56, v57
	v_cvt_pk_bf16_f32 v85, v58, v59
	v_cvt_pk_bf16_f32 v86, v60, v61
	v_cvt_pk_bf16_f32 v87, v62, v63
	global_store_dwordx2 v29, v[80:81], s[10:11]
	global_store_dwordx2 v29, v[82:83], s[10:11] offset:512
	global_store_dwordx2 v29, v[84:85], s[10:11] offset:1024
	global_store_dwordx2 v29, v[86:87], s[10:11] offset:1536
	s_add_u32 s40, s40, 0x800000
	s_addc_u32 s41, s41, 0
	s_waitcnt lgkmcnt(0)
	s_barrier
; #define LAS __attribute__((address_space(3)))
; __device__ __forceinline__ float wave_sum(float v) { for (int o = 32; o >= 1; o >>= 1) v += __shfl_xor(v, o); return v; }
; __device__ __forceinline__ void p0_rows(const Args& a, LAS unsigned char* lds, int gw, int NGW, int wave, int lane, int tid) {
;     ...
;         const f32x4* xr = (const f32x4*)xrow_ptr(a, row) + lane; f32x4 v[4]; float s = 0.f;
; #pragma unroll
;         for (int j = 0; j < 4; ++j) { v[j] = xr[64 * j]; s += (v[j][0] * v[j][0] + v[j][1] * v[j][1]) + (v[j][2] * v[j][2] + v[j][3] * v[j][3]); }
;         const float rstd = rsqrtf(wave_sum(s) * (1.f / DM) + EPS);
;     ...
;         const int jj = lane & 15, p = lane >> 4; float acc = 0.f;
;         const LAS float* hp = hrow + p * 264; const LAS float* wp = WdL + p * 4112 + jj;
; #pragma unroll 8
;         for (int kk = 0; kk < 256; ++kk) acc += hp[kk] * wp[kk * 16];
;         acc += __shfl_xor(acc, 16); acc += __shfl_xor(acc, 32);
;         if (lane < 16) DLR[(size_t)row * 16 + jj] = acc;
	ds_read_b128 v[128:131], v19
	ds_read_b128 v[132:135], v19 offset:16
	ds_read_b128 v[136:139], v19 offset:32
	ds_read_b128 v[140:143], v19 offset:48
	ds_read_b128 v[144:147], v19 offset:64
	ds_read_b128 v[148:151], v19 offset:80
	ds_read_b128 v[152:155], v19 offset:96
	ds_read_b128 v[156:159], v19 offset:112
	s_waitcnt lgkmcnt(7)
	v_mfma_f32_16x16x4_f32 v[160:163], v128, v96, 0
	v_mfma_f32_16x16x4_f32 v[164:167], v129, v97, 0
	v_mfma_f32_16x16x4_f32 v[160:163], v130, v98, v[160:163]
	v_mfma_f32_16x16x4_f32 v[164:167], v131, v99, v[164:167]
	s_waitcnt lgkmcnt(6)
	v_mfma_f32_16x16x4_f32 v[160:163], v132, v100, v[160:163]
	v_mfma_f32_16x16x4_f32 v[164:167], v133, v101, v[164:167]
	v_mfma_f32_16x16x4_f32 v[160:163], v134, v102, v[160:163]
	v_mfma_f32_16x16x4_f32 v[164:167], v135, v103, v[164:167]
	s_waitcnt lgkmcnt(5)
	v_mfma_f32_16x16x4_f32 v[160:163], v136, v104, v[160:163]
	v_mfma_f32_16x16x4_f32 v[164:167], v137, v105, v[164:167]
	v_mfma_f32_16x16x4_f32 v[160:163], v138, v106, v[160:163]
	v_mfma_f32_16x16x4_f32 v[164:167], v139, v107, v[164:167]
	s_waitcnt lgkmcnt(4)
	v_mfma_f32_16x16x4_f32 v[160:163], v140, v108, v[160:163]
	v_mfma_f32_16x16x4_f32 v[164:167], v141, v109, v[164:167]
	v_mfma_f32_16x16x4_f32 v[160:163], v142, v110, v[160:163]
	v_mfma_f32_16x16x4_f32 v[164:167], v143, v111, v[164:167]
	s_waitcnt lgkmcnt(3)
	v_mfma_f32_16x16x4_f32 v[160:163], v144, v112, v[160:163]
	v_mfma_f32_16x16x4_f32 v[164:167], v145, v113, v[164:167]
	v_mfma_f32_16x16x4_f32 v[160:163], v146, v114, v[160:163]
	v_mfma_f32_16x16x4_f32 v[164:167], v147, v115, v[164:167]
	s_waitcnt lgkmcnt(2)
	v_mfma_f32_16x16x4_f32 v[160:163], v148, v116, v[160:163]
	v_mfma_f32_16x16x4_f32 v[164:167], v149, v117, v[164:167]
	v_mfma_f32_16x16x4_f32 v[160:163], v150, v118, v[160:163]
	v_mfma_f32_16x16x4_f32 v[164:167], v151, v119, v[164:167]
	s_waitcnt lgkmcnt(1)
	v_mfma_f32_16x16x4_f32 v[160:163], v152, v120, v[160:163]
	v_mfma_f32_16x16x4_f32 v[164:167], v153, v121, v[164:167]
	v_mfma_f32_16x16x4_f32 v[160:163], v154, v122, v[160:163]
	v_mfma_f32_16x16x4_f32 v[164:167], v155, v123, v[164:167]
	s_waitcnt lgkmcnt(0)
	v_mfma_f32_16x16x4_f32 v[160:163], v156, v124, v[160:163]
	v_mfma_f32_16x16x4_f32 v[164:167], v157, v125, v[164:167]
	v_mfma_f32_16x16x4_f32 v[160:163], v158, v126, v[160:163]
	v_mfma_f32_16x16x4_f32 v[164:167], v159, v127, v[164:167]
	s_nop 9
	v_add_f32_e32 v160, v160, v164
	v_add_f32_e32 v161, v161, v165
	v_add_f32_e32 v162, v162, v166
	v_add_f32_e32 v163, v163, v167
	ds_write_b128 v21, v[160:163]
	s_waitcnt lgkmcnt(0)
	s_barrier
	s_cmp_lt_u32 s93, 4
	s_cbranch_scc0 .Lp0m_s3skip_b2
	ds_read_b32 v168, v22
	ds_read_b32 v169, v22 offset:1024
	ds_read_b32 v170, v22 offset:2048
	ds_read_b32 v171, v22 offset:3072
	ds_read_b32 v172, v22 offset:4096
	ds_read_b32 v173, v22 offset:5120
	ds_read_b32 v174, v22 offset:6144
	ds_read_b32 v175, v22 offset:7168
	s_waitcnt lgkmcnt(6)
	v_add_f32_e32 v168, v168, v169
	s_waitcnt lgkmcnt(5)
	v_add_f32_e32 v168, v168, v170
	s_waitcnt lgkmcnt(4)
	v_add_f32_e32 v168, v168, v171
	s_waitcnt lgkmcnt(3)
	v_add_f32_e32 v168, v168, v172
	s_waitcnt lgkmcnt(2)
	v_add_f32_e32 v168, v168, v173
	s_waitcnt lgkmcnt(1)
	v_add_f32_e32 v168, v168, v174
	s_waitcnt lgkmcnt(0)
	v_add_f32_e32 v168, v168, v175
	global_store_dword v23, v168, s[52:53]
.Lp0m_s3skip_b2:
	v_add_u32_e32 v23, 0x40000, v23
	s_cmpk_lt_i32 s2, 0x80
	s_cbranch_scc0 .Lp0m_tailB
	s_lshl_b32 s10, s81, 12
	s_add_u32 s44, s38, s10
	s_addc_u32 s45, s39, 0
	global_load_dwordx4 v[32:35], v28, s[44:45]
	global_load_dwordx4 v[36:39], v28, s[44:45] offset:1024
	global_load_dwordx4 v[40:43], v28, s[44:45] offset:2048
	global_load_dwordx4 v[44:47], v28, s[44:45] offset:3072
	s_waitcnt vmcnt(12)
	v_mul_f32_e32 v64, v192, v192
	v_fmac_f32_e32 v64, v193, v193
	v_mul_f32_e32 v65, v194, v194
	v_fmac_f32_e32 v65, v195, v195
	v_add_f32_e32 v64, v64, v65
	v_mul_f32_e32 v66, v196, v196
	v_fmac_f32_e32 v66, v197, v197
	v_mul_f32_e32 v67, v198, v198
	v_fmac_f32_e32 v67, v199, v199
	v_add_f32_e32 v66, v66, v67
	v_mul_f32_e32 v68, v200, v200
	v_fmac_f32_e32 v68, v201, v201
	v_mul_f32_e32 v69, v202, v202
	v_fmac_f32_e32 v69, v203, v203
	v_add_f32_e32 v68, v68, v69
	v_mul_f32_e32 v70, v204, v204
	v_fmac_f32_e32 v70, v205, v205
	v_mul_f32_e32 v71, v206, v206
	v_fmac_f32_e32 v71, v207, v207
	v_add_f32_e32 v70, v70, v71
	v_add_f32_e32 v64, v64, v66
	v_add_f32_e32 v64, v64, v68
	v_add_f32_e32 v64, v64, v70
	s_nop 1
	v_add_f32_dpp v88, v64, v64 quad_perm:[1,0,3,2] row_mask:0xf bank_mask:0xf
	s_nop 1
	v_add_f32_dpp v88, v88, v88 quad_perm:[2,3,0,1] row_mask:0xf bank_mask:0xf
	s_nop 1
	v_add_f32_dpp v88, v88, v88 row_half_mirror row_mask:0xf bank_mask:0xf
	s_nop 1
	v_add_f32_dpp v88, v88, v88 row_mirror row_mask:0xf bank_mask:0xf
	s_nop 1
	v_readlane_b32 s48, v88, 0
	v_readlane_b32 s49, v88, 16
	v_readlane_b32 s50, v88, 32
	v_readlane_b32 s51, v88, 48
	s_nop 1
	v_mov_b32_e32 v88, s48
	v_add_f32_e32 v88, s49, v88
	v_add_f32_e32 v88, s50, v88
	v_add_f32_e32 v88, s51, v88
	v_fmamk_f32 v88, v88, 0x3a800000, v16
	v_mul_f32_e32 v89, 0x4b800000, v88
	v_cmp_gt_f32_e64 s[8:9], s3, v88
	s_nop 1
	v_cndmask_b32_e64 v88, v88, v89, s[8:9]
	v_rsq_f32_e32 v88, v88
	s_nop 0
	v_mul_f32_e32 v89, 0x45800000, v88
	v_cndmask_b32_e64 v88, v88, v89, s[8:9]
	v_mul_f32_e32 v192, v192, v88
	v_mul_f32_e32 v193, v193, v88
	v_mul_f32_e32 v194, v194, v88
	v_mul_f32_e32 v195, v195, v88
	v_mul_f32_e32 v196, v196, v88
	v_mul_f32_e32 v197, v197, v88
	v_mul_f32_e32 v198, v198, v88
	v_mul_f32_e32 v199, v199, v88
	v_mul_f32_e32 v200, v200, v88
	v_mul_f32_e32 v201, v201, v88
	v_mul_f32_e32 v202, v202, v88
	v_mul_f32_e32 v203, v203, v88
; #define LAS __attribute__((address_space(3)))
; __device__ __forceinline__ void wave_lds_sync() { asm volatile("s_waitcnt lgkmcnt(0)" ::: "memory"); __builtin_amdgcn_wave_barrier(); }
; __device__ __forceinline__ u32x2 pk4(f32x4 v) { u32x2 w; w.x = cvt_pk_bf16(v[0], v[1]); w.y = cvt_pk_bf16(v[2], v[3]); return w; }
; __device__ __forceinline__ void p0_rows(const Args& a, LAS unsigned char* lds, int gw, int NGW, int wave, int lane, int tid) {
;     ...
;         u32x2* ho = (u32x2*)(H + (size_t)row * DM) + lane;
; #pragma unroll
;         for (int j = 0; j < 4; ++j) { v[j] = v[j] * rstd * g[j]; ho[64 * j] = pk4(v[j]); *(LAS f32x4*)(hrow + j * 264 + 4 * lane) = v[j]; }
;         wave_lds_sync();
	v_mul_f32_e32 v204, v204, v88
	v_mul_f32_e32 v205, v205, v88
	v_mul_f32_e32 v206, v206, v88
	v_mul_f32_e32 v207, v207, v88
	v_mul_f32_e32 v192, v0, v192
	v_mul_f32_e32 v193, v1, v193
	v_mul_f32_e32 v194, v2, v194
	v_mul_f32_e32 v195, v3, v195
	v_mul_f32_e32 v196, v4, v196
	v_mul_f32_e32 v197, v5, v197
	v_mul_f32_e32 v198, v6, v198
	v_mul_f32_e32 v199, v7, v199
	v_mul_f32_e32 v200, v8, v200
	v_mul_f32_e32 v201, v9, v201
	v_mul_f32_e32 v202, v10, v202
	v_mul_f32_e32 v203, v11, v203
	v_mul_f32_e32 v204, v12, v204
	v_mul_f32_e32 v205, v13, v205
	v_mul_f32_e32 v206, v14, v206
	v_mul_f32_e32 v207, v15, v207
	s_add_i32 s7, s42, 65792
	v_add_u32_e32 v18, s7, v17
	ds_write_b128 v18, v[192:195]
	ds_write_b128 v18, v[196:199] offset:1024
	ds_write_b128 v18, v[200:203] offset:2048
	ds_write_b128 v18, v[204:207] offset:3072
	v_cvt_pk_bf16_f32 v80, v192, v193
	v_cvt_pk_bf16_f32 v81, v194, v195
	v_cvt_pk_bf16_f32 v82, v196, v197
	v_cvt_pk_bf16_f32 v83, v198, v199
	v_cvt_pk_bf16_f32 v84, v200, v201
	v_cvt_pk_bf16_f32 v85, v202, v203
	v_cvt_pk_bf16_f32 v86, v204, v205
	v_cvt_pk_bf16_f32 v87, v206, v207
	global_store_dwordx2 v29, v[80:81], s[40:41]
	global_store_dwordx2 v29, v[82:83], s[40:41] offset:512
	global_store_dwordx2 v29, v[84:85], s[40:41] offset:1024
	global_store_dwordx2 v29, v[86:87], s[40:41] offset:1536
	v_mul_f32_e32 v64, v208, v208
	v_fmac_f32_e32 v64, v209, v209
	v_mul_f32_e32 v65, v210, v210
	v_fmac_f32_e32 v65, v211, v211
	v_add_f32_e32 v64, v64, v65
	v_mul_f32_e32 v66, v212, v212
	v_fmac_f32_e32 v66, v213, v213
	v_mul_f32_e32 v67, v214, v214
	v_fmac_f32_e32 v67, v215, v215
	v_add_f32_e32 v66, v66, v67
	v_mul_f32_e32 v68, v216, v216
	v_fmac_f32_e32 v68, v217, v217
	v_mul_f32_e32 v69, v218, v218
	v_fmac_f32_e32 v69, v219, v219
	v_add_f32_e32 v68, v68, v69
	v_mul_f32_e32 v70, v220, v220
	v_fmac_f32_e32 v70, v221, v221
	v_mul_f32_e32 v71, v222, v222
	v_fmac_f32_e32 v71, v223, v223
	v_add_f32_e32 v70, v70, v71
	v_add_f32_e32 v64, v64, v66
	v_add_f32_e32 v64, v64, v68
	v_add_f32_e32 v64, v64, v70
	s_nop 1
	v_add_f32_dpp v88, v64, v64 quad_perm:[1,0,3,2] row_mask:0xf bank_mask:0xf
	s_nop 1
	v_add_f32_dpp v88, v88, v88 quad_perm:[2,3,0,1] row_mask:0xf bank_mask:0xf
	s_nop 1
	v_add_f32_dpp v88, v88, v88 row_half_mirror row_mask:0xf bank_mask:0xf
	s_nop 1
	v_add_f32_dpp v88, v88, v88 row_mirror row_mask:0xf bank_mask:0xf
	s_nop 1
	v_readlane_b32 s48, v88, 0
	v_readlane_b32 s49, v88, 16
	v_readlane_b32 s50, v88, 32
	v_readlane_b32 s51, v88, 48
	s_nop 1
	v_mov_b32_e32 v88, s48
	v_add_f32_e32 v88, s49, v88
	v_add_f32_e32 v88, s50, v88
	v_add_f32_e32 v88, s51, v88
	v_fmamk_f32 v88, v88, 0x3a800000, v16
	v_mul_f32_e32 v89, 0x4b800000, v88
	v_cmp_gt_f32_e64 s[8:9], s3, v88
	s_nop 1
	v_cndmask_b32_e64 v88, v88, v89, s[8:9]
	v_rsq_f32_e32 v88, v88
	s_nop 0
	v_mul_f32_e32 v89, 0x45800000, v88
	v_cndmask_b32_e64 v88, v88, v89, s[8:9]
	v_mul_f32_e32 v208, v208, v88
	v_mul_f32_e32 v209, v209, v88
	v_mul_f32_e32 v210, v210, v88
	v_mul_f32_e32 v211, v211, v88
	v_mul_f32_e32 v212, v212, v88
	v_mul_f32_e32 v213, v213, v88
	v_mul_f32_e32 v214, v214, v88
	v_mul_f32_e32 v215, v215, v88
	v_mul_f32_e32 v216, v216, v88
	v_mul_f32_e32 v217, v217, v88
	v_mul_f32_e32 v218, v218, v88
	v_mul_f32_e32 v219, v219, v88
	v_mul_f32_e32 v220, v220, v88
	v_mul_f32_e32 v221, v221, v88
	v_mul_f32_e32 v222, v222, v88
	v_mul_f32_e32 v223, v223, v88
	v_mul_f32_e32 v208, v0, v208
	v_mul_f32_e32 v209, v1, v209
	v_mul_f32_e32 v210, v2, v210
	v_mul_f32_e32 v211, v3, v211
	v_mul_f32_e32 v212, v4, v212
	v_mul_f32_e32 v213, v5, v213
	v_mul_f32_e32 v214, v6, v214
	v_mul_f32_e32 v215, v7, v215
	v_mul_f32_e32 v216, v8, v216
	v_mul_f32_e32 v217, v9, v217
	v_mul_f32_e32 v218, v10, v218
	v_mul_f32_e32 v219, v11, v219
	v_mul_f32_e32 v220, v12, v220
	v_mul_f32_e32 v221, v13, v221
	v_mul_f32_e32 v222, v14, v222
	v_mul_f32_e32 v223, v15, v223
	s_add_i32 s7, s42, 98688
	v_add_u32_e32 v18, s7, v17
	ds_write_b128 v18, v[208:211]
	ds_write_b128 v18, v[212:215] offset:1024
	ds_write_b128 v18, v[216:219] offset:2048
	ds_write_b128 v18, v[220:223] offset:3072
	s_add_u32 s10, s40, 0x400000
	s_addc_u32 s11, s41, 0
	v_cvt_pk_bf16_f32 v80, v208, v209
	v_cvt_pk_bf16_f32 v81, v210, v211
	v_cvt_pk_bf16_f32 v82, v212, v213
	v_cvt_pk_bf16_f32 v83, v214, v215
	v_cvt_pk_bf16_f32 v84, v216, v217
	v_cvt_pk_bf16_f32 v85, v218, v219
	v_cvt_pk_bf16_f32 v86, v220, v221
	v_cvt_pk_bf16_f32 v87, v222, v223
	global_store_dwordx2 v29, v[80:81], s[10:11]
	global_store_dwordx2 v29, v[82:83], s[10:11] offset:512
	global_store_dwordx2 v29, v[84:85], s[10:11] offset:1024
	global_store_dwordx2 v29, v[86:87], s[10:11] offset:1536
	s_add_u32 s40, s40, 0x800000
	s_addc_u32 s41, s41, 0
	s_waitcnt lgkmcnt(0)
	s_barrier
; #define LAS __attribute__((address_space(3)))
; __device__ __forceinline__ float wave_sum(float v) { for (int o = 32; o >= 1; o >>= 1) v += __shfl_xor(v, o); return v; }
; __device__ __forceinline__ void wave_lds_sync() { asm volatile("s_waitcnt lgkmcnt(0)" ::: "memory"); __builtin_amdgcn_wave_barrier(); }
; __device__ __forceinline__ u32x2 pk4(f32x4 v) { u32x2 w; w.x = cvt_pk_bf16(v[0], v[1]); w.y = cvt_pk_bf16(v[2], v[3]); return w; }
; __device__ __forceinline__ void p0_rows(const Args& a, LAS unsigned char* lds, int gw, int NGW, int wave, int lane, int tid) {
;     ...
;         const f32x4* xr = (const f32x4*)xrow_ptr(a, row) + lane; f32x4 v[4]; float s = 0.f;
; #pragma unroll
;         for (int j = 0; j < 4; ++j) { v[j] = xr[64 * j]; s += (v[j][0] * v[j][0] + v[j][1] * v[j][1]) + (v[j][2] * v[j][2] + v[j][3] * v[j][3]); }
;         const float rstd = rsqrtf(wave_sum(s) * (1.f / DM) + EPS);
;         u32x2* ho = (u32x2*)(H + (size_t)row * DM) + lane;
; #pragma unroll
;         for (int j = 0; j < 4; ++j) { v[j] = v[j] * rstd * g[j]; ho[64 * j] = pk4(v[j]); *(LAS f32x4*)(hrow + j * 264 + 4 * lane) = v[j]; }
;         wave_lds_sync();
;         const int jj = lane & 15, p = lane >> 4; float acc = 0.f;
;         const LAS float* hp = hrow + p * 264; const LAS float* wp = WdL + p * 4112 + jj;
; #pragma unroll 8
;         for (int kk = 0; kk < 256; ++kk) acc += hp[kk] * wp[kk * 16];
;         acc += __shfl_xor(acc, 16); acc += __shfl_xor(acc, 32);
;         if (lane < 16) DLR[(size_t)row * 16 + jj] = acc;
	ds_read_b128 v[128:131], v20
	ds_read_b128 v[132:135], v20 offset:16
	ds_read_b128 v[136:139], v20 offset:32
	ds_read_b128 v[140:143], v20 offset:48
	ds_read_b128 v[144:147], v20 offset:64
	ds_read_b128 v[148:151], v20 offset:80
	ds_read_b128 v[152:155], v20 offset:96
	ds_read_b128 v[156:159], v20 offset:112
	s_waitcnt lgkmcnt(7)
	v_mfma_f32_16x16x4_f32 v[160:163], v128, v96, 0
	v_mfma_f32_16x16x4_f32 v[164:167], v129, v97, 0
	v_mfma_f32_16x16x4_f32 v[160:163], v130, v98, v[160:163]
	v_mfma_f32_16x16x4_f32 v[164:167], v131, v99, v[164:167]
	s_waitcnt lgkmcnt(6)
	v_mfma_f32_16x16x4_f32 v[160:163], v132, v100, v[160:163]
	v_mfma_f32_16x16x4_f32 v[164:167], v133, v101, v[164:167]
	v_mfma_f32_16x16x4_f32 v[160:163], v134, v102, v[160:163]
	v_mfma_f32_16x16x4_f32 v[164:167], v135, v103, v[164:167]
	s_waitcnt lgkmcnt(5)
	v_mfma_f32_16x16x4_f32 v[160:163], v136, v104, v[160:163]
	v_mfma_f32_16x16x4_f32 v[164:167], v137, v105, v[164:167]
	v_mfma_f32_16x16x4_f32 v[160:163], v138, v106, v[160:163]
	v_mfma_f32_16x16x4_f32 v[164:167], v139, v107, v[164:167]
	s_waitcnt lgkmcnt(4)
	v_mfma_f32_16x16x4_f32 v[160:163], v140, v108, v[160:163]
	v_mfma_f32_16x16x4_f32 v[164:167], v141, v109, v[164:167]
	v_mfma_f32_16x16x4_f32 v[160:163], v142, v110, v[160:163]
	v_mfma_f32_16x16x4_f32 v[164:167], v143, v111, v[164:167]
	s_waitcnt lgkmcnt(3)
	v_mfma_f32_16x16x4_f32 v[160:163], v144, v112, v[160:163]
	v_mfma_f32_16x16x4_f32 v[164:167], v145, v113, v[164:167]
	v_mfma_f32_16x16x4_f32 v[160:163], v146, v114, v[160:163]
	v_mfma_f32_16x16x4_f32 v[164:167], v147, v115, v[164:167]
	s_waitcnt lgkmcnt(2)
	v_mfma_f32_16x16x4_f32 v[160:163], v148, v116, v[160:163]
	v_mfma_f32_16x16x4_f32 v[164:167], v149, v117, v[164:167]
	v_mfma_f32_16x16x4_f32 v[160:163], v150, v118, v[160:163]
	v_mfma_f32_16x16x4_f32 v[164:167], v151, v119, v[164:167]
	s_waitcnt lgkmcnt(1)
	v_mfma_f32_16x16x4_f32 v[160:163], v152, v120, v[160:163]
	v_mfma_f32_16x16x4_f32 v[164:167], v153, v121, v[164:167]
	v_mfma_f32_16x16x4_f32 v[160:163], v154, v122, v[160:163]
	v_mfma_f32_16x16x4_f32 v[164:167], v155, v123, v[164:167]
	s_waitcnt lgkmcnt(0)
	v_mfma_f32_16x16x4_f32 v[160:163], v156, v124, v[160:163]
	v_mfma_f32_16x16x4_f32 v[164:167], v157, v125, v[164:167]
	v_mfma_f32_16x16x4_f32 v[160:163], v158, v126, v[160:163]
	v_mfma_f32_16x16x4_f32 v[164:167], v159, v127, v[164:167]
	s_nop 9
	v_add_f32_e32 v160, v160, v164
	v_add_f32_e32 v161, v161, v165
	v_add_f32_e32 v162, v162, v166
	v_add_f32_e32 v163, v163, v167
	ds_write_b128 v21, v[160:163]
	s_waitcnt lgkmcnt(0)
	s_barrier
	s_cmp_lt_u32 s93, 4
	s_cbranch_scc0 .Lp0m_s3skip_b3a
	ds_read_b32 v168, v22
	ds_read_b32 v169, v22 offset:1024
	ds_read_b32 v170, v22 offset:2048
	ds_read_b32 v171, v22 offset:3072
	ds_read_b32 v172, v22 offset:4096
	ds_read_b32 v173, v22 offset:5120
	ds_read_b32 v174, v22 offset:6144
	ds_read_b32 v175, v22 offset:7168
	s_waitcnt lgkmcnt(6)
	v_add_f32_e32 v168, v168, v169
	s_waitcnt lgkmcnt(5)
	v_add_f32_e32 v168, v168, v170
	s_waitcnt lgkmcnt(4)
	v_add_f32_e32 v168, v168, v171
	s_waitcnt lgkmcnt(3)
	v_add_f32_e32 v168, v168, v172
	s_waitcnt lgkmcnt(2)
	v_add_f32_e32 v168, v168, v173
	s_waitcnt lgkmcnt(1)
	v_add_f32_e32 v168, v168, v174
	s_waitcnt lgkmcnt(0)
	v_add_f32_e32 v168, v168, v175
	global_store_dword v23, v168, s[52:53]
.Lp0m_s3skip_b3a:
	v_add_u32_e32 v23, 0x40000, v23
	s_waitcnt vmcnt(8)
	v_mul_f32_e32 v64, v32, v32
	v_fmac_f32_e32 v64, v33, v33
	v_mul_f32_e32 v65, v34, v34
	v_fmac_f32_e32 v65, v35, v35
	v_add_f32_e32 v64, v64, v65
	v_mul_f32_e32 v66, v36, v36
	v_fmac_f32_e32 v66, v37, v37
	v_mul_f32_e32 v67, v38, v38
	v_fmac_f32_e32 v67, v39, v39
	v_add_f32_e32 v66, v66, v67
	v_mul_f32_e32 v68, v40, v40
	v_fmac_f32_e32 v68, v41, v41
	v_mul_f32_e32 v69, v42, v42
	v_fmac_f32_e32 v69, v43, v43
	v_add_f32_e32 v68, v68, v69
	v_mul_f32_e32 v70, v44, v44
	v_fmac_f32_e32 v70, v45, v45
	v_mul_f32_e32 v71, v46, v46
	v_fmac_f32_e32 v71, v47, v47
	v_add_f32_e32 v70, v70, v71
	v_add_f32_e32 v64, v64, v66
	v_add_f32_e32 v64, v64, v68
	v_add_f32_e32 v64, v64, v70
	s_nop 1
	v_add_f32_dpp v88, v64, v64 quad_perm:[1,0,3,2] row_mask:0xf bank_mask:0xf
	s_nop 1
	v_add_f32_dpp v88, v88, v88 quad_perm:[2,3,0,1] row_mask:0xf bank_mask:0xf
	s_nop 1
	v_add_f32_dpp v88, v88, v88 row_half_mirror row_mask:0xf bank_mask:0xf
	s_nop 1
	v_add_f32_dpp v88, v88, v88 row_mirror row_mask:0xf bank_mask:0xf
	s_nop 1
	v_readlane_b32 s48, v88, 0
	v_readlane_b32 s49, v88, 16
	v_readlane_b32 s50, v88, 32
	v_readlane_b32 s51, v88, 48
	s_nop 1
	v_mov_b32_e32 v88, s48
	v_add_f32_e32 v88, s49, v88
	v_add_f32_e32 v88, s50, v88
	v_add_f32_e32 v88, s51, v88
	v_fmamk_f32 v88, v88, 0x3a800000, v16
	v_mul_f32_e32 v89, 0x4b800000, v88
	v_cmp_gt_f32_e64 s[8:9], s3, v88
	s_nop 1
	v_cndmask_b32_e64 v88, v88, v89, s[8:9]
	v_rsq_f32_e32 v88, v88
	s_nop 0
	v_mul_f32_e32 v89, 0x45800000, v88
	v_cndmask_b32_e64 v88, v88, v89, s[8:9]
	v_mul_f32_e32 v32, v32, v88
	v_mul_f32_e32 v33, v33, v88
	v_mul_f32_e32 v34, v34, v88
	v_mul_f32_e32 v35, v35, v88
	v_mul_f32_e32 v36, v36, v88
	v_mul_f32_e32 v37, v37, v88
	v_mul_f32_e32 v38, v38, v88
	v_mul_f32_e32 v39, v39, v88
	v_mul_f32_e32 v40, v40, v88
	v_mul_f32_e32 v41, v41, v88
	v_mul_f32_e32 v42, v42, v88
	v_mul_f32_e32 v43, v43, v88
	v_mul_f32_e32 v44, v44, v88
	v_mul_f32_e32 v45, v45, v88
	v_mul_f32_e32 v46, v46, v88
	v_mul_f32_e32 v47, v47, v88
	v_mul_f32_e32 v32, v0, v32
	v_mul_f32_e32 v33, v1, v33
	v_mul_f32_e32 v34, v2, v34
	v_mul_f32_e32 v35, v3, v35
	v_mul_f32_e32 v36, v4, v36
	v_mul_f32_e32 v37, v5, v37
	v_mul_f32_e32 v38, v6, v38
	v_mul_f32_e32 v39, v7, v39
	v_mul_f32_e32 v40, v8, v40
	v_mul_f32_e32 v41, v9, v41
	v_mul_f32_e32 v42, v10, v42
	v_mul_f32_e32 v43, v11, v43
	v_mul_f32_e32 v44, v12, v44
	v_mul_f32_e32 v45, v13, v45
	v_mul_f32_e32 v46, v14, v46
	v_mul_f32_e32 v47, v15, v47
	s_add_i32 s7, s42, 0
	v_add_u32_e32 v18, s7, v17
	ds_write_b128 v18, v[32:35]
	ds_write_b128 v18, v[36:39] offset:1024
	ds_write_b128 v18, v[40:43] offset:2048
	ds_write_b128 v18, v[44:47] offset:3072
	v_cvt_pk_bf16_f32 v80, v32, v33
	v_cvt_pk_bf16_f32 v81, v34, v35
	v_cvt_pk_bf16_f32 v82, v36, v37
	v_cvt_pk_bf16_f32 v83, v38, v39
	v_cvt_pk_bf16_f32 v84, v40, v41
	v_cvt_pk_bf16_f32 v85, v42, v43
	v_cvt_pk_bf16_f32 v86, v44, v45
	v_cvt_pk_bf16_f32 v87, v46, v47
	global_store_dwordx2 v29, v[80:81], s[40:41]
	global_store_dwordx2 v29, v[82:83], s[40:41] offset:512
	global_store_dwordx2 v29, v[84:85], s[40:41] offset:1024
	global_store_dwordx2 v29, v[86:87], s[40:41] offset:1536
	s_add_u32 s40, s40, 0x800000
	s_addc_u32 s41, s41, 0
	s_waitcnt lgkmcnt(0)
	s_barrier
; #define LAS __attribute__((address_space(3)))
; __device__ __forceinline__ void wave_lds_sync() { asm volatile("s_waitcnt lgkmcnt(0)" ::: "memory"); __builtin_amdgcn_wave_barrier(); }
; __device__ __forceinline__ void p0_rows(const Args& a, LAS unsigned char* lds, int gw, int NGW, int wave, int lane, int tid) {
;     ...
;         const int jj = lane & 15, p = lane >> 4; float acc = 0.f;
;         const LAS float* hp = hrow + p * 264; const LAS float* wp = WdL + p * 4112 + jj;
; #pragma unroll 8
;         for (int kk = 0; kk < 256; ++kk) acc += hp[kk] * wp[kk * 16];
;         acc += __shfl_xor(acc, 16); acc += __shfl_xor(acc, 32);
;         if (lane < 16) DLR[(size_t)row * 16 + jj] = acc;
;         wave_lds_sync();
;     }
	ds_read_b128 v[128:131], v19
	ds_read_b128 v[132:135], v19 offset:16
	ds_read_b128 v[136:139], v19 offset:32
	ds_read_b128 v[140:143], v19 offset:48
	ds_read_b128 v[144:147], v19 offset:64
	ds_read_b128 v[148:151], v19 offset:80
	ds_read_b128 v[152:155], v19 offset:96
	ds_read_b128 v[156:159], v19 offset:112
	s_waitcnt lgkmcnt(7)
	v_mfma_f32_16x16x4_f32 v[160:163], v128, v96, 0
	v_mfma_f32_16x16x4_f32 v[164:167], v129, v97, 0
	v_mfma_f32_16x16x4_f32 v[160:163], v130, v98, v[160:163]
	v_mfma_f32_16x16x4_f32 v[164:167], v131, v99, v[164:167]
	s_waitcnt lgkmcnt(6)
	v_mfma_f32_16x16x4_f32 v[160:163], v132, v100, v[160:163]
	v_mfma_f32_16x16x4_f32 v[164:167], v133, v101, v[164:167]
	v_mfma_f32_16x16x4_f32 v[160:163], v134, v102, v[160:163]
	v_mfma_f32_16x16x4_f32 v[164:167], v135, v103, v[164:167]
	s_waitcnt lgkmcnt(5)
	v_mfma_f32_16x16x4_f32 v[160:163], v136, v104, v[160:163]
	v_mfma_f32_16x16x4_f32 v[164:167], v137, v105, v[164:167]
	v_mfma_f32_16x16x4_f32 v[160:163], v138, v106, v[160:163]
	v_mfma_f32_16x16x4_f32 v[164:167], v139, v107, v[164:167]
	s_waitcnt lgkmcnt(4)
	v_mfma_f32_16x16x4_f32 v[160:163], v140, v108, v[160:163]
	v_mfma_f32_16x16x4_f32 v[164:167], v141, v109, v[164:167]
	v_mfma_f32_16x16x4_f32 v[160:163], v142, v110, v[160:163]
	v_mfma_f32_16x16x4_f32 v[164:167], v143, v111, v[164:167]
	s_waitcnt lgkmcnt(3)
	v_mfma_f32_16x16x4_f32 v[160:163], v144, v112, v[160:163]
	v_mfma_f32_16x16x4_f32 v[164:167], v145, v113, v[164:167]
	v_mfma_f32_16x16x4_f32 v[160:163], v146, v114, v[160:163]
	v_mfma_f32_16x16x4_f32 v[164:167], v147, v115, v[164:167]
	s_waitcnt lgkmcnt(2)
	v_mfma_f32_16x16x4_f32 v[160:163], v148, v116, v[160:163]
	v_mfma_f32_16x16x4_f32 v[164:167], v149, v117, v[164:167]
	v_mfma_f32_16x16x4_f32 v[160:163], v150, v118, v[160:163]
	v_mfma_f32_16x16x4_f32 v[164:167], v151, v119, v[164:167]
	s_waitcnt lgkmcnt(1)
	v_mfma_f32_16x16x4_f32 v[160:163], v152, v120, v[160:163]
	v_mfma_f32_16x16x4_f32 v[164:167], v153, v121, v[164:167]
	v_mfma_f32_16x16x4_f32 v[160:163], v154, v122, v[160:163]
	v_mfma_f32_16x16x4_f32 v[164:167], v155, v123, v[164:167]
	s_waitcnt lgkmcnt(0)
	v_mfma_f32_16x16x4_f32 v[160:163], v156, v124, v[160:163]
	v_mfma_f32_16x16x4_f32 v[164:167], v157, v125, v[164:167]
	v_mfma_f32_16x16x4_f32 v[160:163], v158, v126, v[160:163]
	v_mfma_f32_16x16x4_f32 v[164:167], v159, v127, v[164:167]
	s_nop 9
	v_add_f32_e32 v160, v160, v164
	v_add_f32_e32 v161, v161, v165
	v_add_f32_e32 v162, v162, v166
	v_add_f32_e32 v163, v163, v167
	ds_write_b128 v21, v[160:163]
	s_waitcnt lgkmcnt(0)
	s_barrier
	s_cmp_lt_u32 s93, 2
	s_cbranch_scc0 .Lp0m_s3skip_b4
	ds_read_b32 v168, v22
	ds_read_b32 v169, v22 offset:1024
	ds_read_b32 v170, v22 offset:2048
	ds_read_b32 v171, v22 offset:3072
	ds_read_b32 v172, v22 offset:4096
	ds_read_b32 v173, v22 offset:5120
	ds_read_b32 v174, v22 offset:6144
	ds_read_b32 v175, v22 offset:7168
	s_waitcnt lgkmcnt(6)
	v_add_f32_e32 v168, v168, v169
	s_waitcnt lgkmcnt(5)
	v_add_f32_e32 v168, v168, v170
	s_waitcnt lgkmcnt(4)
	v_add_f32_e32 v168, v168, v171
	s_waitcnt lgkmcnt(3)
	v_add_f32_e32 v168, v168, v172
	s_waitcnt lgkmcnt(2)
	v_add_f32_e32 v168, v168, v173
	s_waitcnt lgkmcnt(1)
	v_add_f32_e32 v168, v168, v174
	s_waitcnt lgkmcnt(0)
	v_add_f32_e32 v168, v168, v175
	global_store_dword v23, v168, s[52:53]
.Lp0m_s3skip_b4:
	v_add_u32_e32 v23, 0x40000, v23
	s_branch .LBB0_144
.Lp0m_tailB:
	s_waitcnt vmcnt(8)
	v_mul_f32_e32 v64, v192, v192
	v_fmac_f32_e32 v64, v193, v193
	v_mul_f32_e32 v65, v194, v194
	v_fmac_f32_e32 v65, v195, v195
	v_add_f32_e32 v64, v64, v65
	v_mul_f32_e32 v66, v196, v196
	v_fmac_f32_e32 v66, v197, v197
	v_mul_f32_e32 v67, v198, v198
	v_fmac_f32_e32 v67, v199, v199
	v_add_f32_e32 v66, v66, v67
	v_mul_f32_e32 v68, v200, v200
	v_fmac_f32_e32 v68, v201, v201
	v_mul_f32_e32 v69, v202, v202
	v_fmac_f32_e32 v69, v203, v203
	v_add_f32_e32 v68, v68, v69
	v_mul_f32_e32 v70, v204, v204
	v_fmac_f32_e32 v70, v205, v205
	v_mul_f32_e32 v71, v206, v206
	v_fmac_f32_e32 v71, v207, v207
	v_add_f32_e32 v70, v70, v71
	v_add_f32_e32 v64, v64, v66
	v_add_f32_e32 v64, v64, v68
	v_add_f32_e32 v64, v64, v70
	s_nop 1
	v_add_f32_dpp v88, v64, v64 quad_perm:[1,0,3,2] row_mask:0xf bank_mask:0xf
	s_nop 1
	v_add_f32_dpp v88, v88, v88 quad_perm:[2,3,0,1] row_mask:0xf bank_mask:0xf
	s_nop 1
	v_add_f32_dpp v88, v88, v88 row_half_mirror row_mask:0xf bank_mask:0xf
	s_nop 1
	v_add_f32_dpp v88, v88, v88 row_mirror row_mask:0xf bank_mask:0xf
	s_nop 1
	v_readlane_b32 s48, v88, 0
	v_readlane_b32 s49, v88, 16
	v_readlane_b32 s50, v88, 32
	v_readlane_b32 s51, v88, 48
	s_nop 1
	v_mov_b32_e32 v88, s48
	v_add_f32_e32 v88, s49, v88
	v_add_f32_e32 v88, s50, v88
	v_add_f32_e32 v88, s51, v88
	v_fmamk_f32 v88, v88, 0x3a800000, v16
	v_mul_f32_e32 v89, 0x4b800000, v88
	v_cmp_gt_f32_e64 s[8:9], s3, v88
	s_nop 1
	v_cndmask_b32_e64 v88, v88, v89, s[8:9]
	v_rsq_f32_e32 v88, v88
	s_nop 0
	v_mul_f32_e32 v89, 0x45800000, v88
	v_cndmask_b32_e64 v88, v88, v89, s[8:9]
	v_mul_f32_e32 v192, v192, v88
	v_mul_f32_e32 v193, v193, v88
	v_mul_f32_e32 v194, v194, v88
	v_mul_f32_e32 v195, v195, v88
	v_mul_f32_e32 v196, v196, v88
	v_mul_f32_e32 v197, v197, v88
	v_mul_f32_e32 v198, v198, v88
	v_mul_f32_e32 v199, v199, v88
	v_mul_f32_e32 v200, v200, v88
	v_mul_f32_e32 v201, v201, v88
	v_mul_f32_e32 v202, v202, v88
	v_mul_f32_e32 v203, v203, v88
	v_mul_f32_e32 v204, v204, v88
	v_mul_f32_e32 v205, v205, v88
	v_mul_f32_e32 v206, v206, v88
	v_mul_f32_e32 v207, v207, v88
	v_mul_f32_e32 v192, v0, v192
	v_mul_f32_e32 v193, v1, v193
	v_mul_f32_e32 v194, v2, v194
	v_mul_f32_e32 v195, v3, v195
	v_mul_f32_e32 v196, v4, v196
	v_mul_f32_e32 v197, v5, v197
	v_mul_f32_e32 v198, v6, v198
; #define LAS __attribute__((address_space(3)))
; __device__ __forceinline__ void wave_lds_sync() { asm volatile("s_waitcnt lgkmcnt(0)" ::: "memory"); __builtin_amdgcn_wave_barrier(); }
; __device__ __forceinline__ u32x2 pk4(f32x4 v) { u32x2 w; w.x = cvt_pk_bf16(v[0], v[1]); w.y = cvt_pk_bf16(v[2], v[3]); return w; }
; __device__ __forceinline__ void p0_rows(const Args& a, LAS unsigned char* lds, int gw, int NGW, int wave, int lane, int tid) {
;     ...
;         u32x2* ho = (u32x2*)(H + (size_t)row * DM) + lane;
; #pragma unroll
;         for (int j = 0; j < 4; ++j) { v[j] = v[j] * rstd * g[j]; ho[64 * j] = pk4(v[j]); *(LAS f32x4*)(hrow + j * 264 + 4 * lane) = v[j]; }
;         wave_lds_sync();
	v_mul_f32_e32 v199, v7, v199
	v_mul_f32_e32 v200, v8, v200
	v_mul_f32_e32 v201, v9, v201
	v_mul_f32_e32 v202, v10, v202
	v_mul_f32_e32 v203, v11, v203
	v_mul_f32_e32 v204, v12, v204
	v_mul_f32_e32 v205, v13, v205
	v_mul_f32_e32 v206, v14, v206
	v_mul_f32_e32 v207, v15, v207
	s_add_i32 s7, s42, 65792
	v_add_u32_e32 v18, s7, v17
	ds_write_b128 v18, v[192:195]
	ds_write_b128 v18, v[196:199] offset:1024
	ds_write_b128 v18, v[200:203] offset:2048
	ds_write_b128 v18, v[204:207] offset:3072
	v_cvt_pk_bf16_f32 v80, v192, v193
	v_cvt_pk_bf16_f32 v81, v194, v195
	v_cvt_pk_bf16_f32 v82, v196, v197
	v_cvt_pk_bf16_f32 v83, v198, v199
	v_cvt_pk_bf16_f32 v84, v200, v201
	v_cvt_pk_bf16_f32 v85, v202, v203
	v_cvt_pk_bf16_f32 v86, v204, v205
	v_cvt_pk_bf16_f32 v87, v206, v207
	global_store_dwordx2 v29, v[80:81], s[40:41]
	global_store_dwordx2 v29, v[82:83], s[40:41] offset:512
	global_store_dwordx2 v29, v[84:85], s[40:41] offset:1024
	global_store_dwordx2 v29, v[86:87], s[40:41] offset:1536
	v_mul_f32_e32 v64, v208, v208
	v_fmac_f32_e32 v64, v209, v209
	v_mul_f32_e32 v65, v210, v210
	v_fmac_f32_e32 v65, v211, v211
	v_add_f32_e32 v64, v64, v65
	v_mul_f32_e32 v66, v212, v212
	v_fmac_f32_e32 v66, v213, v213
	v_mul_f32_e32 v67, v214, v214
	v_fmac_f32_e32 v67, v215, v215
	v_add_f32_e32 v66, v66, v67
	v_mul_f32_e32 v68, v216, v216
	v_fmac_f32_e32 v68, v217, v217
	v_mul_f32_e32 v69, v218, v218
	v_fmac_f32_e32 v69, v219, v219
	v_add_f32_e32 v68, v68, v69
	v_mul_f32_e32 v70, v220, v220
	v_fmac_f32_e32 v70, v221, v221
	v_mul_f32_e32 v71, v222, v222
	v_fmac_f32_e32 v71, v223, v223
	v_add_f32_e32 v70, v70, v71
	v_add_f32_e32 v64, v64, v66
	v_add_f32_e32 v64, v64, v68
	v_add_f32_e32 v64, v64, v70
	s_nop 1
	v_add_f32_dpp v88, v64, v64 quad_perm:[1,0,3,2] row_mask:0xf bank_mask:0xf
	s_nop 1
	v_add_f32_dpp v88, v88, v88 quad_perm:[2,3,0,1] row_mask:0xf bank_mask:0xf
	s_nop 1
	v_add_f32_dpp v88, v88, v88 row_half_mirror row_mask:0xf bank_mask:0xf
	s_nop 1
	v_add_f32_dpp v88, v88, v88 row_mirror row_mask:0xf bank_mask:0xf
	s_nop 1
	v_readlane_b32 s48, v88, 0
	v_readlane_b32 s49, v88, 16
	v_readlane_b32 s50, v88, 32
	v_readlane_b32 s51, v88, 48
	s_nop 1
	v_mov_b32_e32 v88, s48
	v_add_f32_e32 v88, s49, v88
	v_add_f32_e32 v88, s50, v88
	v_add_f32_e32 v88, s51, v88
	v_fmamk_f32 v88, v88, 0x3a800000, v16
	v_mul_f32_e32 v89, 0x4b800000, v88
	v_cmp_gt_f32_e64 s[8:9], s3, v88
	s_nop 1
	v_cndmask_b32_e64 v88, v88, v89, s[8:9]
	v_rsq_f32_e32 v88, v88
	s_nop 0
	v_mul_f32_e32 v89, 0x45800000, v88
	v_cndmask_b32_e64 v88, v88, v89, s[8:9]
	v_mul_f32_e32 v208, v208, v88
	v_mul_f32_e32 v209, v209, v88
	v_mul_f32_e32 v210, v210, v88
	v_mul_f32_e32 v211, v211, v88
	v_mul_f32_e32 v212, v212, v88
	v_mul_f32_e32 v213, v213, v88
	v_mul_f32_e32 v214, v214, v88
	v_mul_f32_e32 v215, v215, v88
	v_mul_f32_e32 v216, v216, v88
	v_mul_f32_e32 v217, v217, v88
	v_mul_f32_e32 v218, v218, v88
	v_mul_f32_e32 v219, v219, v88
	v_mul_f32_e32 v220, v220, v88
	v_mul_f32_e32 v221, v221, v88
	v_mul_f32_e32 v222, v222, v88
	v_mul_f32_e32 v223, v223, v88
	v_mul_f32_e32 v208, v0, v208
	v_mul_f32_e32 v209, v1, v209
	v_mul_f32_e32 v210, v2, v210
	v_mul_f32_e32 v211, v3, v211
	v_mul_f32_e32 v212, v4, v212
	v_mul_f32_e32 v213, v5, v213
	v_mul_f32_e32 v214, v6, v214
	v_mul_f32_e32 v215, v7, v215
	v_mul_f32_e32 v216, v8, v216
	v_mul_f32_e32 v217, v9, v217
	v_mul_f32_e32 v218, v10, v218
	v_mul_f32_e32 v219, v11, v219
	v_mul_f32_e32 v220, v12, v220
	v_mul_f32_e32 v221, v13, v221
	v_mul_f32_e32 v222, v14, v222
	v_mul_f32_e32 v223, v15, v223
	s_add_i32 s7, s42, 98688
	v_add_u32_e32 v18, s7, v17
	ds_write_b128 v18, v[208:211]
	ds_write_b128 v18, v[212:215] offset:1024
	ds_write_b128 v18, v[216:219] offset:2048
	ds_write_b128 v18, v[220:223] offset:3072
	s_add_u32 s10, s40, 0x400000
	s_addc_u32 s11, s41, 0
	v_cvt_pk_bf16_f32 v80, v208, v209
	v_cvt_pk_bf16_f32 v81, v210, v211
	v_cvt_pk_bf16_f32 v82, v212, v213
	v_cvt_pk_bf16_f32 v83, v214, v215
	v_cvt_pk_bf16_f32 v84, v216, v217
	v_cvt_pk_bf16_f32 v85, v218, v219
	v_cvt_pk_bf16_f32 v86, v220, v221
	v_cvt_pk_bf16_f32 v87, v222, v223
	global_store_dwordx2 v29, v[80:81], s[10:11]
	global_store_dwordx2 v29, v[82:83], s[10:11] offset:512
	global_store_dwordx2 v29, v[84:85], s[10:11] offset:1024
	global_store_dwordx2 v29, v[86:87], s[10:11] offset:1536
	s_add_u32 s40, s40, 0x800000
	s_addc_u32 s41, s41, 0
	s_waitcnt lgkmcnt(0)
	s_barrier
; #define LAS __attribute__((address_space(3)))
; __device__ __forceinline__ void p0_rows(const Args& a, LAS unsigned char* lds, int gw, int NGW, int wave, int lane, int tid) {
;     ...
;         const int jj = lane & 15, p = lane >> 4; float acc = 0.f;
;         const LAS float* hp = hrow + p * 264; const LAS float* wp = WdL + p * 4112 + jj;
; #pragma unroll 8
;         for (int kk = 0; kk < 256; ++kk) acc += hp[kk] * wp[kk * 16];
;         acc += __shfl_xor(acc, 16); acc += __shfl_xor(acc, 32);
;         if (lane < 16) DLR[(size_t)row * 16 + jj] = acc;
	ds_read_b128 v[128:131], v20
	ds_read_b128 v[132:135], v20 offset:16
	ds_read_b128 v[136:139], v20 offset:32
	ds_read_b128 v[140:143], v20 offset:48
	ds_read_b128 v[144:147], v20 offset:64
	ds_read_b128 v[148:151], v20 offset:80
	ds_read_b128 v[152:155], v20 offset:96
	ds_read_b128 v[156:159], v20 offset:112
	s_waitcnt lgkmcnt(7)
	v_mfma_f32_16x16x4_f32 v[160:163], v128, v96, 0
	v_mfma_f32_16x16x4_f32 v[164:167], v129, v97, 0
	v_mfma_f32_16x16x4_f32 v[160:163], v130, v98, v[160:163]
	v_mfma_f32_16x16x4_f32 v[164:167], v131, v99, v[164:167]
	s_waitcnt lgkmcnt(6)
	v_mfma_f32_16x16x4_f32 v[160:163], v132, v100, v[160:163]
	v_mfma_f32_16x16x4_f32 v[164:167], v133, v101, v[164:167]
	v_mfma_f32_16x16x4_f32 v[160:163], v134, v102, v[160:163]
	v_mfma_f32_16x16x4_f32 v[164:167], v135, v103, v[164:167]
	s_waitcnt lgkmcnt(5)
	v_mfma_f32_16x16x4_f32 v[160:163], v136, v104, v[160:163]
	v_mfma_f32_16x16x4_f32 v[164:167], v137, v105, v[164:167]
	v_mfma_f32_16x16x4_f32 v[160:163], v138, v106, v[160:163]
	v_mfma_f32_16x16x4_f32 v[164:167], v139, v107, v[164:167]
	s_waitcnt lgkmcnt(4)
	v_mfma_f32_16x16x4_f32 v[160:163], v140, v108, v[160:163]
	v_mfma_f32_16x16x4_f32 v[164:167], v141, v109, v[164:167]
	v_mfma_f32_16x16x4_f32 v[160:163], v142, v110, v[160:163]
	v_mfma_f32_16x16x4_f32 v[164:167], v143, v111, v[164:167]
	s_waitcnt lgkmcnt(3)
	v_mfma_f32_16x16x4_f32 v[160:163], v144, v112, v[160:163]
	v_mfma_f32_16x16x4_f32 v[164:167], v145, v113, v[164:167]
	v_mfma_f32_16x16x4_f32 v[160:163], v146, v114, v[160:163]
	v_mfma_f32_16x16x4_f32 v[164:167], v147, v115, v[164:167]
	s_waitcnt lgkmcnt(2)
	v_mfma_f32_16x16x4_f32 v[160:163], v148, v116, v[160:163]
	v_mfma_f32_16x16x4_f32 v[164:167], v149, v117, v[164:167]
	v_mfma_f32_16x16x4_f32 v[160:163], v150, v118, v[160:163]
	v_mfma_f32_16x16x4_f32 v[164:167], v151, v119, v[164:167]
	s_waitcnt lgkmcnt(1)
	v_mfma_f32_16x16x4_f32 v[160:163], v152, v120, v[160:163]
	v_mfma_f32_16x16x4_f32 v[164:167], v153, v121, v[164:167]
	v_mfma_f32_16x16x4_f32 v[160:163], v154, v122, v[160:163]
	v_mfma_f32_16x16x4_f32 v[164:167], v155, v123, v[164:167]
	s_waitcnt lgkmcnt(0)
	v_mfma_f32_16x16x4_f32 v[160:163], v156, v124, v[160:163]
	v_mfma_f32_16x16x4_f32 v[164:167], v157, v125, v[164:167]
	v_mfma_f32_16x16x4_f32 v[160:163], v158, v126, v[160:163]
	v_mfma_f32_16x16x4_f32 v[164:167], v159, v127, v[164:167]
	s_nop 9
	v_add_f32_e32 v160, v160, v164
	v_add_f32_e32 v161, v161, v165
	v_add_f32_e32 v162, v162, v166
	v_add_f32_e32 v163, v163, v167
	ds_write_b128 v21, v[160:163]
	s_waitcnt lgkmcnt(0)
	s_barrier
	s_cmp_lt_u32 s93, 4
	s_cbranch_scc0 .Lp0m_s3skip_b3b
	ds_read_b32 v168, v22
	ds_read_b32 v169, v22 offset:1024
	ds_read_b32 v170, v22 offset:2048
	ds_read_b32 v171, v22 offset:3072
	ds_read_b32 v172, v22 offset:4096
	ds_read_b32 v173, v22 offset:5120
	ds_read_b32 v174, v22 offset:6144
	ds_read_b32 v175, v22 offset:7168
	s_waitcnt lgkmcnt(6)
	v_add_f32_e32 v168, v168, v169
	s_waitcnt lgkmcnt(5)
	v_add_f32_e32 v168, v168, v170
	s_waitcnt lgkmcnt(4)
	v_add_f32_e32 v168, v168, v171
	s_waitcnt lgkmcnt(3)
	v_add_f32_e32 v168, v168, v172
	s_waitcnt lgkmcnt(2)
	v_add_f32_e32 v168, v168, v173
	s_waitcnt lgkmcnt(1)
	v_add_f32_e32 v168, v168, v174
	s_waitcnt lgkmcnt(0)
	v_add_f32_e32 v168, v168, v175
	global_store_dword v23, v168, s[52:53]
